# rec_pass1 cumulative log-decays kept in the log2 domain: the per-exp multiply by log2(e) removed (170 sites), clamps rescaled, HGRN prologue and GLA 1/16 constant produce log2-domain sums
# speedup vs baseline: 1.0063x; 1.0053x over previous
.LBB0_190:
	s_cmpk_gt_i32 s20, 0xff
	s_mov_b64 s[2:3], -1
	s_cbranch_scc0 .LBB0_292
	s_lshl_b32 s6, s20, 1
	s_cmpk_gt_u32 s20, 0x2ff
	s_cbranch_scc0 .LBB0_231
	v_mov_b32_e32 v0, v206
	s_add_i32 s2, s6, 0xfffffa00
	v_ashrrev_i32_e32 v0, 8, v0
	v_mov_b32_e32 v106, v206
	v_mov_b32_e32 v111, v206
	v_add_u32_e32 v102, s2, v0
	v_readlane_b32 s4, v254, 15
	v_readlane_b32 s5, v254, 16
	v_lshlrev_b32_e32 v144, 6, v102
	v_and_b32_e32 v144, 0x1fc0, v144
	v_lshrrev_b32_e32 v145, 9, v102
	v_lshl_or_b32 v144, v145, 13, v144
	v_bfe_u32 v145, v206, 6, 2
	v_lshl_add_u32 v144, v145, 4, v144
	v_and_b32_e32 v145, 15, v206
	v_or_b32_e32 v144, v144, v145
	v_bfe_u32 v145, v206, 4, 2
	v_lshlrev_b32_e32 v144, 6, v144
	v_lshl_add_u32 v144, v145, 4, v144
	v_bfe_u32 v146, v102, 7, 2
	v_lshlrev_b32_e32 v146, 7, v146
	v_lshl_add_u32 v146, v145, 11, v146
	v_and_b32_e32 v147, 15, v206
	v_lshl_add_u32 v146, v147, 2, v146
	global_load_dwordx4 v[140:143], v144, s[4:5]
	global_load_dword v118, v146, s[82:83]
	global_load_dword v119, v146, s[82:83] offset:64
	global_load_dword v120, v146, s[82:83] offset:512
	global_load_dword v121, v146, s[82:83] offset:576
	global_load_dword v122, v146, s[82:83] offset:1024
	global_load_dword v123, v146, s[82:83] offset:1088
	global_load_dword v124, v146, s[82:83] offset:1536
	global_load_dword v125, v146, s[82:83] offset:1600
	v_mov_b32_e32 v1, v206
	v_bfe_u32 v2, v111, 6, 2
	s_movk_i32 s2, 0x100
	v_ashrrev_i32_e32 v0, 9, v102
	v_xor_b32_e32 v3, 3, v2
	v_cmp_gt_u32_e32 vcc, s2, v1
	v_ashrrev_i32_e32 v1, 31, v0
	v_and_b32_e32 v107, 15, v111
	v_cndmask_b32_e32 v108, v3, v2, vcc
	v_lshlrev_b64 v[100:101], 13, v[0:1]
	v_lshlrev_b32_e32 v0, 6, v102
	s_movk_i32 s2, 0x1fc0
	v_lshlrev_b32_e32 v113, 4, v108
	v_and_or_b32 v12, v0, s2, v100
	v_or_b32_e32 v110, v113, v107
	v_or_b32_e32 v100, v12, v110
	v_mov_b64_e32 v[0:1], s[68:69]
	v_bfe_u32 v8, v102, 7, 2
	v_mad_u64_u32 v[0:1], s[2:3], v100, s13, v[0:1]
	v_bfe_u32 v112, v111, 4, 2
	v_mad_i32_i24 v1, v101, s13, v1
	v_lshlrev_b32_e32 v176, 6, v8
	v_lshl_add_u64 v[0:1], v[0:1], 0, v[176:177]
	v_lshlrev_b32_e32 v2, 4, v112
	v_mov_b32_e32 v3, v177
	v_lshl_add_u64 v[0:1], v[0:1], 0, v[2:3]
	s_mov_b32 s2, 0x3e80000
	v_add_co_u32_e32 v0, vcc, s2, v0
	v_mov_b32_e32 v115, v206
	s_nop 0
	v_addc_co_u32_e32 v1, vcc, 0, v1, vcc
	global_load_dwordx4 v[0:3], v[0:1], off offset:3584
	v_lshlrev_b32_e32 v104, 7, v8
	v_bfe_u32 v116, v115, 2, 6
	v_lshlrev_b32_e32 v4, 4, v115
	v_and_b32_e32 v117, 48, v4
	v_or_b32_e32 v6, v12, v116
	v_mov_b64_e32 v[4:5], s[76:77]
	v_bfe_u32 v103, v115, 5, 3
	v_mad_u64_u32 v[6:7], s[2:3], v6, s13, v[4:5]
	v_mad_i32_i24 v7, v101, s13, v7
	v_mov_b32_e32 v105, v177
	v_lshlrev_b32_e32 v114, 3, v103
	v_lshlrev_b32_e32 v109, 5, v8
	v_lshl_add_u64 v[6:7], v[6:7], 0, v[104:105]
	v_lshlrev_b32_e32 v8, 1, v117
	v_mov_b32_e32 v9, v177
	v_or_b32_e32 v167, 1, v114
	v_lshl_add_u64 v[6:7], v[6:7], 0, v[8:9]
	s_mov_b64 s[2:3], 0x1000
	v_or_b32_e32 v8, v114, v12
	v_or_b32_e32 v12, v12, v167
	v_mov_b32_e32 v13, v101
	v_lshl_add_u64 v[158:159], v[6:7], 0, s[2:3]
	v_lshlrev_b64 v[14:15], 6, v[12:13]
	v_mad_u64_u32 v[12:13], s[2:3], v12, s13, v[4:5]
	v_and_b32_e32 v166, 31, v115
	v_mov_b32_e32 v9, v101
	v_readlane_b32 s4, v254, 15
	v_mad_i32_i24 v13, v101, s13, v13
	v_lshlrev_b64 v[10:11], 6, v[8:9]
	v_readlane_b32 s5, v254, 16
	v_lshlrev_b32_e32 v40, 1, v166
	v_mov_b32_e32 v41, v177
	v_lshl_add_u64 v[12:13], v[12:13], 0, v[176:177]
	v_lshl_add_u64 v[154:155], s[4:5], 0, v[10:11]
	v_lshl_add_u64 v[14:15], s[4:5], 0, v[14:15]
	v_lshl_add_u64 v[42:43], v[12:13], 0, v[40:41]
	v_or_b32_e32 v12, 2, v8
	v_mov_b32_e32 v13, v101
	v_lshlrev_b64 v[14:15], 6, v[12:13]
	v_mad_u64_u32 v[12:13], s[2:3], v12, s13, v[4:5]
	v_mad_i32_i24 v13, v101, s13, v13
	v_lshl_add_u64 v[12:13], v[12:13], 0, v[176:177]
	v_lshl_add_u64 v[58:59], v[12:13], 0, v[40:41]
	v_or_b32_e32 v12, 3, v8
	v_mov_b32_e32 v13, v101
	v_lshl_add_u64 v[56:57], s[4:5], 0, v[14:15]
	v_lshlrev_b64 v[14:15], 6, v[12:13]
	v_mad_u64_u32 v[12:13], s[2:3], v12, s13, v[4:5]
	v_mad_i32_i24 v13, v101, s13, v13
	v_lshl_add_u64 v[12:13], v[12:13], 0, v[176:177]
	v_lshl_add_u64 v[14:15], s[4:5], 0, v[14:15]
	v_lshl_add_u64 v[84:85], v[12:13], 0, v[40:41]
	v_or_b32_e32 v12, 4, v8
	v_mov_b32_e32 v13, v101
	v_lshlrev_b64 v[14:15], 6, v[12:13]
	v_mad_u64_u32 v[12:13], s[2:3], v12, s13, v[4:5]
	v_mad_i32_i24 v13, v101, s13, v13
	v_lshl_add_u64 v[12:13], v[12:13], 0, v[176:177]
	v_lshl_add_u64 v[156:157], v[12:13], 0, v[40:41]
	v_or_b32_e32 v12, 5, v8
	v_mov_b32_e32 v13, v101
	v_lshl_add_u64 v[86:87], s[4:5], 0, v[14:15]
	v_lshlrev_b64 v[14:15], 6, v[12:13]
	v_mad_u64_u32 v[12:13], s[2:3], v12, s13, v[4:5]
	v_mad_i32_i24 v13, v101, s13, v13
	v_lshl_add_u64 v[12:13], v[12:13], 0, v[176:177]
	v_lshl_add_u64 v[14:15], s[4:5], 0, v[14:15]
	v_lshl_add_u64 v[160:161], v[12:13], 0, v[40:41]
	v_or_b32_e32 v12, 6, v8
	v_mov_b32_e32 v13, v101
	v_mad_u64_u32 v[10:11], s[2:3], v8, s13, v[4:5]
	v_lshlrev_b64 v[14:15], 6, v[12:13]
	v_mad_u64_u32 v[12:13], s[2:3], v12, s13, v[4:5]
	v_or_b32_e32 v8, 7, v8
	v_mad_i32_i24 v13, v101, s13, v13
	v_mad_u64_u32 v[4:5], s[2:3], v8, s13, v[4:5]
	v_mad_i32_i24 v11, v101, s13, v11
	v_lshl_add_u64 v[12:13], v[12:13], 0, v[176:177]
	v_mad_i32_i24 v5, v101, s13, v5
	s_movk_i32 s2, 0x1000
	v_lshl_add_u64 v[10:11], v[10:11], 0, v[176:177]
	v_lshl_add_u64 v[164:165], v[12:13], 0, v[40:41]
	v_lshlrev_b64 v[12:13], 6, v[8:9]
	v_lshl_add_u64 v[4:5], v[4:5], 0, v[176:177]
	v_add_co_u32_e32 v6, vcc, s2, v6
	v_lshl_add_u64 v[10:11], v[10:11], 0, v[40:41]
	v_lshl_add_u64 v[162:163], s[4:5], 0, v[14:15]
	v_lshl_add_u64 v[24:25], s[4:5], 0, v[12:13]
	v_lshl_add_u64 v[4:5], v[4:5], 0, v[40:41]
	v_addc_co_u32_e32 v7, vcc, 0, v7, vcc
	s_nop 0
	s_nop 0
	global_load_ushort v168, v[10:11], off offset:3840
	global_load_ushort v169, v[42:43], off offset:3840
	global_load_ushort v170, v[58:59], off offset:3840
	global_load_ushort v171, v[84:85], off offset:3840
	s_nop 0
	s_nop 0
	global_load_ushort v172, v[156:157], off offset:3840
	global_load_ushort v173, v[160:161], off offset:3840
	s_nop 0
	global_load_ushort v162, v[164:165], off offset:3840
	global_load_ushort v163, v[4:5], off offset:3840
	global_load_dwordx4 v[8:11], v[6:7], off
	s_nop 0
	s_nop 0
	global_load_dwordx4 v[4:7], v[158:159], off offset:16
	v_lshl_add_u64 v[158:159], s[82:83], 0, v[104:105]
	v_lshlrev_b32_e32 v104, 2, v166
	v_or3_b32 v160, v109, s8, v166
	v_lshl_add_u64 v[158:159], v[158:159], 0, v[104:105]
	v_ashrrev_i32_e32 v161, 31, v160
	v_add_co_u32_e32 v158, vcc, s2, v158
	v_lshl_add_u64 v[160:161], v[160:161], 2, s[50:51]
	s_nop 0
	v_addc_co_u32_e32 v159, vcc, 0, v159, vcc
	global_load_dword v160, v[160:161], off
	s_nop 0
	s_nop 0
	s_waitcnt vmcnt(0)
	s_barrier
	s_mov_b32 s3, 0xbfb8aa3b
	s_mov_b32 s2, 0x3db8aa3b
	v_cmp_gt_u32_sdwa s[4:5], v115, v219 src0_sel:BYTE_0 src1_sel:DWORD
	v_mfma_f32_16x16x4_f32 v[128:131], v140, v118, 0
	v_mfma_f32_16x16x4_f32 v[128:131], v141, v120, v[128:131]
	v_mfma_f32_16x16x4_f32 v[128:131], v142, v122, v[128:131]
	v_mfma_f32_16x16x4_f32 v[128:131], v143, v124, v[128:131]
	v_mfma_f32_16x16x4_f32 v[132:135], v140, v119, 0
	v_mfma_f32_16x16x4_f32 v[132:135], v141, v121, v[132:135]
	v_mfma_f32_16x16x4_f32 v[132:135], v142, v123, v[132:135]
	v_mfma_f32_16x16x4_f32 v[132:135], v143, v125, v[132:135]
	s_nop 15
	s_nop 15
	s_nop 7
	v_permlane16_swap_b32 v128, v132
	v_permlane16_swap_b32 v129, v133
	v_permlane16_swap_b32 v130, v134
	v_permlane16_swap_b32 v131, v135
	v_add_f32_e32 v118, v128, v160
	v_mul_f32_e64 v105, |v118|, s3
	v_exp_f32_e32 v105, v105
	v_add_f32_e32 v68, v131, v160
	v_add_f32_e32 v105, 1.0, v105
	v_mul_f32_e64 v69, |v68|, s3
	v_log_f32_e32 v120, v105
	v_exp_f32_e32 v69, v69
	v_add_f32_e32 v36, v133, v160
	v_mul_f32_e64 v37, |v36|, s3
	v_exp_f32_e32 v37, v37
	v_min_f32_e32 v118, 0, v118
	v_fmac_f32_e32 v118, 0xbf317218, v120
	v_mul_u32_u24_e32 v123, 0x108, v103
	v_add_f32_e32 v69, 1.0, v69
	v_lshrrev_b32_e32 v119, 8, v106
	v_fma_f32 v118, v118, s2, 0
	v_add_lshl_u32 v123, v123, v166, 2
	s_mov_b32 s2, 0xd800
	v_log_f32_e32 v69, v69
	v_lshlrev_b32_e32 v120, 16, v168
	v_add_f32_e32 v121, v129, v160
	v_mad_i32_i24 v123, v119, s2, v123
	v_add_f32_e32 v37, 1.0, v37
	v_mul_f32_e64 v122, |v121|, s3
	ds_write2st64_b32 v123, v118, v120 offset1:68
	v_min_f32_e32 v120, 0, v121
	v_log_f32_e32 v37, v37
	v_min_f32_e32 v68, 0, v68
	v_fmac_f32_e32 v68, 0xbf317218, v69
	v_min_f32_e32 v36, 0, v36
	v_fmac_f32_e32 v36, 0xbf317218, v37
	v_add_f32_e32 v88, v130, v160
	v_exp_f32_e32 v122, v122
	v_mul_f32_e64 v89, |v88|, s3
	v_exp_f32_e32 v89, v89
	v_add_f32_e32 v60, v132, v160
	v_mul_f32_e64 v61, |v60|, s3
	v_exp_f32_e32 v61, v61
	v_add_f32_e32 v28, v134, v160
	v_add_f32_e32 v122, 1.0, v122
	v_mul_f32_e64 v29, |v28|, s3
	v_add_f32_e32 v12, v135, v160
	v_log_f32_e32 v122, v122
	v_add_f32_e32 v89, 1.0, v89
	v_exp_f32_e32 v29, v29
	v_mul_f32_e64 v13, |v12|, s3
	v_log_f32_e32 v89, v89
	v_exp_f32_e32 v13, v13
	v_add_f32_e32 v61, 1.0, v61
	v_log_f32_e32 v61, v61
	v_fmac_f32_e32 v120, 0xbf317218, v122
	v_mul_u32_u24_e32 v91, 33, v167
	v_min_f32_e32 v88, 0, v88
	v_add_f32_e32 v29, 1.0, v29
	v_fmac_f32_e32 v118, 0x3db8aa3b, v120
	v_add_lshl_u32 v91, v91, v166, 2
	v_fmac_f32_e32 v88, 0xbf317218, v89
	v_log_f32_e32 v29, v29
	v_add_f32_e32 v13, 1.0, v13
	v_mad_i32_i24 v91, v119, s2, v91
	v_fmamk_f32 v71, v88, 0x3db8aa3b, v118
	v_min_f32_e32 v60, 0, v60
	v_log_f32_e32 v13, v13
	ds_write2_b32 v91, v118, v71 offset1:33
	v_fmac_f32_e32 v71, 0x3db8aa3b, v68
	v_fmac_f32_e32 v60, 0xbf317218, v61
	v_lshlrev_b32_e32 v90, 16, v169
	v_lshlrev_b32_e32 v70, 16, v170
	v_add_u32_e32 v72, 0x4400, v91
	v_fmamk_f32 v39, v60, 0x3db8aa3b, v71
	v_min_f32_e32 v28, 0, v28
	ds_write2_b32 v72, v90, v70 offset1:33
	v_lshlrev_b32_e32 v62, 16, v171
	v_lshlrev_b32_e32 v38, 16, v172
	ds_write2_b32 v91, v71, v39 offset0:66 offset1:99
	ds_write2_b32 v72, v62, v38 offset0:66 offset1:99
	v_fmac_f32_e32 v39, 0x3db8aa3b, v36
	v_fmac_f32_e32 v28, 0xbf317218, v29
	v_min_f32_e32 v12, 0, v12
	v_fmamk_f32 v15, v28, 0x3db8aa3b, v39
	v_fmac_f32_e32 v12, 0xbf317218, v13
	v_mul_i32_i24_e32 v105, 0xd800, v119
	v_lshlrev_b32_e32 v30, 16, v173
	v_lshlrev_b32_e32 v14, 16, v162
	ds_write2_b32 v91, v39, v15 offset0:132 offset1:165
	ds_write2_b32 v72, v30, v14 offset0:132 offset1:165
	v_fmac_f32_e32 v15, 0x3db8aa3b, v12
	v_lshlrev_b32_e32 v12, 8, v103
	v_or3_b32 v12, v105, v12, v104
	v_lshlrev_b32_e32 v13, 16, v163
	ds_write_b32 v91, v15 offset:792
	ds_write_b32 v91, v13 offset:18200
	ds_write_b32 v12, v15 offset:53248
	v_mul_u32_u24_e32 v12, 0x48, v117
	v_lshlrev_b32_e32 v12, 1, v12
	v_mad_i32_i24 v12, v119, s2, v12
	v_mov_b32_e32 v106, 0
	v_lshl_or_b32 v12, v116, 1, v12
	ds_write_b16 v12, v8 offset:34816
	ds_write_b16_d16_hi v12, v8 offset:34960
	ds_write_b16 v12, v9 offset:35104
	ds_write_b16_d16_hi v12, v9 offset:35248
	ds_write_b16 v12, v10 offset:35392
	ds_write_b16_d16_hi v12, v10 offset:35536
	ds_write_b16 v12, v11 offset:35680
	ds_write_b16_d16_hi v12, v11 offset:35824
	ds_write_b16 v12, v4 offset:35968
	ds_write_b16_d16_hi v12, v4 offset:36112
	ds_write_b16 v12, v5 offset:36256
	ds_write_b16_d16_hi v12, v5 offset:36400
	ds_write_b16 v12, v6 offset:36544
	ds_write_b16_d16_hi v12, v6 offset:36688
	ds_write_b16 v12, v7 offset:36832
	ds_write_b16_d16_hi v12, v7 offset:36976
	s_waitcnt lgkmcnt(0)
	s_barrier
	s_and_saveexec_b64 s[2:3], s[4:5]
	s_cbranch_execz .LBB0_196
	s_mov_b32 s4, 0xd000
	v_add3_u32 v4, v105, v104, s4
	v_mov_b32_e32 v106, 0
	ds_read_b32 v220, v4
	ds_read_b32 v221, v4 offset:256
	ds_read_b32 v222, v4 offset:512
	ds_read_b32 v223, v4 offset:768
	ds_read_b32 v224, v4 offset:1024
	ds_read_b32 v225, v4 offset:1280
	ds_read_b32 v226, v4 offset:1536
	s_waitcnt lgkmcnt(0)
	v_add_f32_e32 v106, v106, v220
	v_cmp_lt_u32_e32 vcc, 1, v103
	s_nop 1
	v_cndmask_b32_e32 v221, 0, v221, vcc
	v_add_f32_e32 v106, v106, v221
	v_cmp_lt_u32_e32 vcc, 2, v103
	s_nop 1
	v_cndmask_b32_e32 v222, 0, v222, vcc
	v_add_f32_e32 v106, v106, v222
	v_cmp_lt_u32_e32 vcc, 3, v103
	s_nop 1
	v_cndmask_b32_e32 v223, 0, v223, vcc
	v_add_f32_e32 v106, v106, v223
	v_cmp_lt_u32_e32 vcc, 4, v103
	s_nop 1
	v_cndmask_b32_e32 v224, 0, v224, vcc
	v_add_f32_e32 v106, v106, v224
	v_cmp_lt_u32_e32 vcc, 5, v103
	s_nop 1
	v_cndmask_b32_e32 v225, 0, v225, vcc
	v_add_f32_e32 v106, v106, v225
	v_cmp_lt_u32_e32 vcc, 6, v103
	s_nop 1
	v_cndmask_b32_e32 v226, 0, v226, vcc
	v_add_f32_e32 v106, v106, v226
	v_mov_b32_e32 v103, 0
.LBB0_196:
	s_or_b64 exec, exec, s[2:3]
	v_mul_u32_u24_e32 v4, 0x84, v114
	v_add3_u32 v6, v105, v104, v4
	ds_read2_b32 v[228:229], v6 offset1:33
	ds_read2_b32 v[230:231], v6 offset0:66 offset1:99
	ds_read2_b32 v[232:233], v6 offset0:132 offset1:165
	ds_read2_b32 v[234:235], v6 offset0:198 offset1:231
	s_movk_i32 s2, 0x90
	v_bfe_u32 v7, v111, 5, 3
	v_lshlrev_b32_e32 v8, 4, v7
	v_mul_u32_u24_e32 v7, 0x420, v7
	v_lshlrev_b32_e32 v15, 3, v112
	s_waitcnt lgkmcnt(0)
	v_pk_add_f32 v[228:229], v[106:107], v[228:229] op_sel_hi:[0,1]
	v_pk_add_f32 v[230:231], v[106:107], v[230:231] op_sel_hi:[0,1]
	v_pk_add_f32 v[232:233], v[106:107], v[232:233] op_sel_hi:[0,1]
	v_pk_add_f32 v[234:235], v[106:107], v[234:235] op_sel_hi:[0,1]
	ds_write2_b32 v6, v228, v229 offset1:33
	ds_write2_b32 v6, v230, v231 offset0:66 offset1:99
	ds_write2_b32 v6, v232, v233 offset0:132 offset1:165
	ds_write2_b32 v6, v234, v235 offset0:198 offset1:231
	v_and_b32_e32 v5, 31, v111
	v_lshlrev_b32_e32 v6, 2, v5
	v_add_u32_e32 v4, v105, v6
	s_waitcnt lgkmcnt(0)
	s_barrier
	ds_read_b32 v4, v4 offset:8316
	v_mad_u32_u24 v5, v5, s2, v105
	s_mov_b32 s2, 0xac00
	v_add3_u32 v5, v5, v8, s2
	v_add3_u32 v6, v105, v7, v6
	v_add_u32_e32 v199, 0x210, v6
	v_add_u32_e32 v200, 0x4400, v6
	v_add_u32_e32 v201, 0x4610, v6
	ds_read2_b32 v[236:237], v200 offset1:33
	ds_read2_b32 v[238:239], v6 offset1:33
	ds_read2_b32 v[240:241], v200 offset0:66 offset1:99
	ds_read2_b32 v[242:243], v6 offset0:66 offset1:99
	ds_read2_b32 v[244:245], v201 offset1:33
	ds_read2_b32 v[246:247], v199 offset1:33
	ds_read2_b32 v[248:249], v201 offset0:66 offset1:99
	ds_read2_b32 v[250:251], v199 offset0:66 offset1:99
	s_waitcnt lgkmcnt(0)
	v_sub_f32_e32 v238, v4, v238
	v_sub_f32_e32 v239, v4, v239
	v_sub_f32_e32 v242, v4, v242
	v_sub_f32_e32 v243, v4, v243
	s_nop 0
	s_nop 0
	s_nop 0
	s_nop 0
	v_exp_f32_e32 v238, v238
	v_exp_f32_e32 v239, v239
	v_exp_f32_e32 v242, v242
	v_exp_f32_e32 v243, v243
	s_nop 0
	v_mul_f32_e32 v238, v236, v238
	v_mul_f32_e32 v239, v237, v239
	v_mul_f32_e32 v242, v240, v242
	v_mul_f32_e32 v243, v241, v243
	v_cvt_pk_bf16_f32 v236, v238, v239
	v_cvt_pk_bf16_f32 v237, v242, v243
	ds_write_b64 v5, v[236:237]
	v_sub_f32_e32 v246, v4, v246
	v_sub_f32_e32 v247, v4, v247
	v_sub_f32_e32 v250, v4, v250
	v_sub_f32_e32 v251, v4, v251
	s_nop 0
	s_nop 0
	s_nop 0
	s_nop 0
	v_exp_f32_e32 v246, v246
	v_exp_f32_e32 v247, v247
	v_exp_f32_e32 v250, v250
	v_exp_f32_e32 v251, v251
	s_nop 0
	v_mul_f32_e32 v246, v244, v246
	v_mul_f32_e32 v247, v245, v247
	v_mul_f32_e32 v250, v248, v250
	v_mul_f32_e32 v251, v249, v251
	v_cvt_pk_bf16_f32 v244, v246, v247
	v_cvt_pk_bf16_f32 v245, v250, v251
	ds_write_b64 v5, v[244:245] offset:8
	v_lshl_add_u32 v8, v15, 1, v105
	s_movk_i32 s2, 0x90
	v_mad_u32_u24 v12, v110, s2, v8
	s_waitcnt lgkmcnt(0)
	s_barrier
	ds_read_b128 v[4:7], v12 offset:34816
	v_mad_u32_u24 v13, v107, s2, v8
	ds_read_b128 v[8:11], v13 offset:44032
	ds_read_b128 v[16:19], v13 offset:46336
	ds_read_b128 v[20:23], v12 offset:34880
	ds_read_b128 v[24:27], v13 offset:46400
	s_waitcnt lgkmcnt(3)
	v_mfma_f32_16x16x32_bf16 v[8:11], v[8:11], v[4:7], 0
	v_ashrrev_i32_e32 v103, 31, v102
	v_readlane_b32 s2, v254, 17
	v_readlane_b32 s3, v254, 18
	s_waitcnt lgkmcnt(2)
	v_mfma_f32_16x16x32_bf16 v[4:7], v[16:19], v[4:7], 0
	ds_read_b128 v[16:19], v13 offset:44096
	v_mov_b32_e32 v13, v177
	v_cmp_lt_u32_sdwa s[4:5], v111, v218 src0_sel:BYTE_0 src1_sel:DWORD
	s_waitcnt lgkmcnt(1)
	v_mfma_f32_16x16x32_bf16 v[4:7], v[24:27], v[20:23], v[4:7]
	v_lshlrev_b32_e32 v24, 2, v112
	s_waitcnt lgkmcnt(0)
	v_mfma_f32_16x16x32_bf16 v[16:19], v[16:19], v[20:23], v[8:11]
	s_nop 2
	v_or_b32_e32 v198, v113, v107
	v_lshl_or_b32 v198, v198, 5, v24
	v_lshlrev_b32_e32 v196, 2, v198
	v_mov_b32_e32 v197, v177
	v_or_b32_e32 v11, v113, v24
	v_lshlrev_b32_e32 v11, 5, v11
	v_lshlrev_b64 v[8:9], 13, v[102:103]
	v_or_b32_e32 v12, v11, v107
	v_lshl_add_u64 v[8:9], s[2:3], 0, v[8:9]
	v_lshl_add_u64 v[196:197], v[8:9], 0, v[196:197]
	v_lshlrev_b32_e32 v12, 2, v12
	v_or_b32_e32 v10, 16, v107
	v_lshl_add_u64 v[12:13], v[8:9], 0, v[12:13]
	global_store_dwordx4 v[196:197], v[16:19], off sc1
	global_store_dwordx4 v[196:197], v[4:7], off offset:64 sc1
	s_nop 1
	v_or_b32_e32 v4, v11, v10
	v_lshlrev_b32_e32 v12, 2, v4
	v_mov_b32_e32 v13, v177
	v_lshl_add_u64 v[8:9], v[8:9], 0, v[12:13]
	s_and_saveexec_b64 s[2:3], s[4:5]
	s_cbranch_execz .LBB0_200
	v_lshlrev_b32_sdwa v4, v213, v111 dst_sel:DWORD dst_unused:UNUSED_PAD src0_sel:DWORD src1_sel:BYTE_0
	v_add_u32_e32 v5, v105, v4
	ds_read_b32 v5, v5 offset:8316
	v_readlane_b32 s4, v254, 19
	v_lshlrev_b64 v[6:7], 7, v[102:103]
	v_readlane_b32 s5, v254, 20
	s_waitcnt lgkmcnt(0)
	s_nop 0
	v_exp_f32_e32 v8, v5
	v_lshl_add_u64 v[6:7], s[4:5], 0, v[6:7]
	v_mov_b32_e32 v5, v177
	v_lshl_add_u64 v[4:5], v[6:7], 0, v[4:5]
	global_store_dword v[4:5], v8, off
.LBB0_200:
	s_or_b64 exec, exec, s[2:3]
	s_movk_i32 s2, 0x840
	v_mad_u32_u24 v12, v108, s2, v105
	v_add_u32_e32 v4, 0xffffff7c, v12
	v_cmp_eq_u32_e64 s[36:37], 0, v108
	v_cmp_ne_u32_e32 vcc, 0, v108
	v_mov_b32_e32 v25, 0
	v_lshl_add_u32 v14, v15, 2, v4
	v_mov_b32_e32 v26, 0
	s_and_saveexec_b64 s[2:3], vcc
	ds_read_b32 v26, v14
	s_or_b64 exec, exec, s[2:3]
	v_lshlrev_b32_e32 v13, 2, v15
	s_and_saveexec_b64 s[2:3], vcc
	s_movk_i32 s4, 0xff80
	v_add3_u32 v4, v12, v13, s4
	ds_read_b32 v25, v4
	s_or_b64 exec, exec, s[2:3]
	v_mul_u32_u24_e32 v4, 0x84, v110
	v_add3_u32 v11, v105, v4, v13
	ds_read2_b32 v[4:5], v11 offset1:1
	v_mov_b32_e32 v27, 0
	v_mov_b32_e32 v28, 0
	s_and_saveexec_b64 s[2:3], vcc
	ds_read_b32 v28, v14 offset:8
	s_or_b64 exec, exec, s[2:3]
	s_and_saveexec_b64 s[2:3], vcc
	s_movk_i32 s4, 0xff88
	v_add3_u32 v6, v12, v13, s4
	ds_read_b32 v27, v6
	s_or_b64 exec, exec, s[2:3]
	ds_read2_b32 v[6:7], v11 offset0:2 offset1:3
	v_mov_b32_e32 v20, 0
	v_mov_b32_e32 v21, 0
	s_and_saveexec_b64 s[2:3], vcc
	ds_read_b32 v21, v14 offset:16
	s_or_b64 exec, exec, s[2:3]
	s_and_saveexec_b64 s[2:3], vcc
	s_movk_i32 s4, 0xff90
	v_add3_u32 v8, v12, v13, s4
	ds_read_b32 v20, v8
	s_or_b64 exec, exec, s[2:3]
	ds_read2_b32 v[8:9], v11 offset0:4 offset1:5
	v_mov_b32_e32 v22, 0
	v_mov_b32_e32 v23, 0
	s_and_saveexec_b64 s[2:3], vcc
	ds_read_b32 v23, v14 offset:24
	s_or_b64 exec, exec, s[2:3]
	s_and_saveexec_b64 s[2:3], vcc
	s_movk_i32 s4, 0xff98
	v_add3_u32 v12, v12, v13, s4
	ds_read_b32 v22, v12
	s_or_b64 exec, exec, s[2:3]
	s_waitcnt lgkmcnt(2)
	v_sub_f32_e32 v12, v4, v26
	v_sub_f32_e32 v13, v5, v25
	s_nop 0
	s_nop 0
	v_exp_f32_e32 v4, v4
	v_exp_f32_e32 v5, v5
	s_nop 0
	s_nop 0
	v_exp_f32_e32 v12, v12
	v_exp_f32_e32 v13, v13
	v_lshlrev_b32_e32 v16, 16, v0
	v_and_b32_e32 v17, 0xffff0000, v0
	s_mov_b32 s2, 0x3e3504f3
	v_pk_mul_f32 v[16:17], v[16:17], s[2:3] op_sel_hi:[1,0]
	s_movk_i32 s4, 0x300
	v_pk_mul_f32 v[4:5], v[16:17], v[4:5]
	v_pk_mul_f32 v[12:13], v[16:17], v[12:13]
	v_cvt_pk_bf16_f32 v4, v4, v5
	s_waitcnt lgkmcnt(1)
	v_sub_f32_e32 v5, v6, v28
	s_nop 0
	v_cvt_pk_bf16_f32 v0, v12, v13
	v_exp_f32_e32 v12, v5
	v_sub_f32_e32 v5, v7, v27
	s_nop 0
	v_exp_f32_e32 v13, v5
	v_mov_b32_e32 v5, v6
	v_exp_f32_e32 v6, v5
	v_mov_b32_e32 v5, v7
	v_exp_f32_e32 v7, v5
	v_lshlrev_b32_e32 v16, 16, v1
	v_and_b32_e32 v17, 0xffff0000, v1
	v_pk_mul_f32 v[16:17], v[16:17], s[2:3] op_sel_hi:[1,0]
	v_or_b32_e32 v31, 2, v24
	v_pk_mul_f32 v[6:7], v[16:17], v[6:7]
	v_pk_mul_f32 v[12:13], v[16:17], v[12:13]
	v_cvt_pk_bf16_f32 v5, v6, v7
	s_waitcnt lgkmcnt(0)
	v_sub_f32_e32 v6, v8, v21
	v_sub_f32_e32 v7, v9, v20
	s_nop 0
	s_nop 0
	v_exp_f32_e32 v6, v6
	v_exp_f32_e32 v7, v7
	s_nop 0
	s_nop 0
	v_exp_f32_e32 v8, v8
	v_exp_f32_e32 v9, v9
	v_cvt_pk_bf16_f32 v1, v12, v13
	v_lshlrev_b32_e32 v12, 16, v2
	v_and_b32_e32 v13, 0xffff0000, v2
	v_pk_mul_f32 v[12:13], v[12:13], s[2:3] op_sel_hi:[1,0]
	v_lshlrev_b32_e32 v16, 16, v3
	v_pk_mul_f32 v[6:7], v[12:13], v[6:7]
	v_and_b32_e32 v17, 0xffff0000, v3
	v_cvt_pk_bf16_f32 v2, v6, v7
	v_pk_mul_f32 v[6:7], v[12:13], v[8:9]
	ds_read2_b32 v[8:9], v11 offset0:6 offset1:7
	v_cvt_pk_bf16_f32 v6, v6, v7
	v_pk_mul_f32 v[16:17], v[16:17], s[2:3] op_sel_hi:[1,0]
	v_or_b32_e32 v30, 3, v24
	s_waitcnt lgkmcnt(0)
	v_sub_f32_e32 v7, v8, v23
	s_nop 0
	v_exp_f32_e32 v12, v7
	v_sub_f32_e32 v7, v9, v22
	s_nop 0
	v_exp_f32_e32 v13, v7
	v_mov_b32_e32 v7, v8
	v_exp_f32_e32 v8, v7
	v_mov_b32_e32 v7, v9
	v_exp_f32_e32 v9, v7
	v_pk_mul_f32 v[12:13], v[16:17], v[12:13]
	v_pk_mul_f32 v[8:9], v[16:17], v[8:9]
	s_nop 0
	v_cvt_pk_bf16_f32 v7, v8, v9
	v_mov_b64_e32 v[8:9], s[68:69]
	v_mad_u64_u32 v[8:9], s[2:3], v100, s4, v[8:9]
	v_cvt_pk_bf16_f32 v3, v12, v13
	v_mov_b32_e32 v12, v9
	v_mad_u64_u32 v[12:13], s[2:3], v101, s4, v[12:13]
	v_mov_b32_e32 v9, v12
	v_lshlrev_b32_e32 v12, 1, v109
	v_mov_b32_e32 v13, v177
	v_lshl_add_u64 v[8:9], v[8:9], 0, v[12:13]
	v_lshlrev_b32_e32 v12, 1, v15
	v_lshl_add_u64 v[8:9], v[8:9], 0, v[12:13]
	s_mov_b32 s2, 0xece4000
	v_add_co_u32_e64 v8, s[38:39], s2, v8
	s_nop 1
	v_addc_co_u32_e64 v9, s[38:39], 0, v9, s[38:39]
	global_store_dwordx4 v[8:9], v[4:7], off offset:512 sc1
	s_nop 1
	v_mad_u32_u24 v4, v107, 33, v15
	v_lshl_add_u32 v29, v4, 2, v105
	ds_read2_b32 v[4:5], v29 offset1:1
	v_add_u32_e32 v6, 0x4400, v29
	ds_read2_b32 v[6:7], v6 offset1:1
	s_waitcnt lgkmcnt(1)
	v_sub_f32_e32 v4, v26, v4
	v_sub_f32_e32 v5, v25, v5
	v_min_f32_e32 v4, 0x42e6d4ca, v4
	v_min_f32_e32 v5, 0x42e6d4ca, v5
	s_nop 0
	s_nop 0
	v_exp_f32_e32 v4, v4
	v_exp_f32_e32 v5, v5
	s_waitcnt lgkmcnt(0)
	v_pk_mul_f32 v[4:5], v[6:7], v[4:5]
	ds_read2_b32 v[6:7], v29 offset0:2 offset1:3
	v_cvt_pk_bf16_f32 v4, v4, v5
	v_add_u32_e32 v5, 0x4408, v29
	ds_read2_b32 v[8:9], v5 offset1:1
	s_waitcnt lgkmcnt(1)
	v_sub_f32_e32 v6, v28, v6
	v_sub_f32_e32 v7, v27, v7
	v_min_f32_e32 v6, 0x42e6d4ca, v6
	v_min_f32_e32 v7, 0x42e6d4ca, v7
	s_nop 0
	s_nop 0
	v_exp_f32_e32 v6, v6
	v_exp_f32_e32 v7, v7
	s_waitcnt lgkmcnt(0)
	v_pk_mul_f32 v[6:7], v[8:9], v[6:7]
	s_nop 0
	v_cvt_pk_bf16_f32 v5, v6, v7
	ds_read2_b32 v[6:7], v29 offset0:4 offset1:5
	v_add_u32_e32 v8, 0x4410, v29
	ds_read2_b32 v[8:9], v8 offset1:1
	s_waitcnt lgkmcnt(1)
	v_sub_f32_e32 v6, v21, v6
	v_sub_f32_e32 v7, v20, v7
	v_min_f32_e32 v6, 0x42e6d4ca, v6
	v_min_f32_e32 v7, 0x42e6d4ca, v7
	s_nop 0
	s_nop 0
	v_exp_f32_e32 v6, v6
	v_exp_f32_e32 v7, v7
	s_waitcnt lgkmcnt(0)
	v_pk_mul_f32 v[6:7], v[8:9], v[6:7]
	ds_read2_b32 v[8:9], v29 offset0:6 offset1:7
	v_cvt_pk_bf16_f32 v6, v6, v7
	v_add_u32_e32 v7, 0x4418, v29
	ds_read2_b32 v[12:13], v7 offset1:1
	s_waitcnt lgkmcnt(1)
	v_sub_f32_e32 v8, v23, v8
	v_sub_f32_e32 v9, v22, v9
	v_min_f32_e32 v8, 0x42e6d4ca, v8
	v_min_f32_e32 v9, 0x42e6d4ca, v9
	s_nop 0
	s_nop 0
	v_exp_f32_e32 v8, v8
	v_exp_f32_e32 v9, v9
	s_waitcnt lgkmcnt(0)
	v_pk_mul_f32 v[8:9], v[12:13], v[8:9]
	s_nop 0
	v_cvt_pk_bf16_f32 v7, v8, v9
	v_mov_b32_e32 v8, 0
	s_nop 0
	v_mfma_f32_16x16x32_bf16 v[4:7], v[4:7], v[0:3], 0
	s_and_saveexec_b64 s[2:3], s[36:37]
	v_cmp_gt_u32_e64 s[36:37], v24, v107
	s_nop 5
	v_cndmask_b32_e64 v9, v4, 0, s[36:37]
	v_cmp_lt_u32_e64 s[36:37], v24, v107
	s_nop 1
	v_cndmask_b32_e64 v4, v9, v4, s[36:37]
	v_cndmask_b32_e64 v5, 0, v5, s[36:37]
	v_cmp_le_u32_e64 s[36:37], v31, v107
	s_nop 1
	v_cndmask_b32_e64 v6, 0, v6, s[36:37]
	v_cmp_le_u32_e64 s[36:37], v30, v107
	s_nop 1
	v_cndmask_b32_e64 v7, 0, v7, s[36:37]
	s_or_b64 exec, exec, s[2:3]
	v_mov_b32_e32 v16, 0
	v_mov_b32_e32 v17, 0
	v_mov_b32_e32 v18, 0
	v_mov_b32_e32 v19, 0
	s_and_saveexec_b64 s[4:5], vcc
	s_cbranch_execz .LBB0_222
	v_mad_u32_u24 v9, v10, 33, v15
	v_lshl_add_u32 v9, v9, 2, v105
	ds_read2_b32 v[200:201], v9 offset1:1
	v_add_u32_e32 v253, 0x4400, v9
	ds_read2_b32 v[202:203], v253 offset1:1
	ds_read2_b32 v[204:205], v9 offset0:2 offset1:3
	v_add_u32_e32 v252, 0x4408, v9
	ds_read2_b32 v[220:221], v252 offset1:1
	ds_read2_b32 v[222:223], v9 offset0:4 offset1:5
	v_add_u32_e32 v251, 0x4410, v9
	ds_read2_b32 v[224:225], v251 offset1:1
	ds_read2_b32 v[226:227], v9 offset0:6 offset1:7
	v_add_u32_e32 v250, 0x4418, v9
	ds_read2_b32 v[228:229], v250 offset1:1
	v_cmp_eq_u32_e32 vcc, 1, v108
	s_waitcnt lgkmcnt(1)
	v_sub_f32_e32 v10, v26, v200
	v_sub_f32_e32 v11, v25, v201
	v_min_f32_e32 v10, 0x42e6d4ca, v10
	v_min_f32_e32 v11, 0x42e6d4ca, v11
	s_nop 0
	s_nop 0
	v_exp_f32_e32 v10, v10
	v_exp_f32_e32 v11, v11
	s_waitcnt lgkmcnt(0)
	v_pk_mul_f32 v[10:11], v[202:203], v[10:11]
	v_cvt_pk_bf16_f32 v10, v10, v11
	s_waitcnt lgkmcnt(1)
	v_sub_f32_e32 v12, v28, v204
	v_sub_f32_e32 v13, v27, v205
	v_min_f32_e32 v12, 0x42e6d4ca, v12
	v_min_f32_e32 v13, 0x42e6d4ca, v13
	s_nop 0
	s_nop 0
	v_exp_f32_e32 v12, v12
	v_exp_f32_e32 v13, v13
	s_waitcnt lgkmcnt(0)
	v_pk_mul_f32 v[12:13], v[220:221], v[12:13]
	s_nop 0
	v_cvt_pk_bf16_f32 v11, v12, v13
	s_waitcnt lgkmcnt(1)
	v_sub_f32_e32 v12, v21, v222
	v_sub_f32_e32 v13, v20, v223
	v_min_f32_e32 v12, 0x42e6d4ca, v12
	v_min_f32_e32 v13, 0x42e6d4ca, v13
	s_nop 0
	s_nop 0
	v_exp_f32_e32 v12, v12
	v_exp_f32_e32 v13, v13
	s_waitcnt lgkmcnt(0)
	v_pk_mul_f32 v[12:13], v[224:225], v[12:13]
	v_cvt_pk_bf16_f32 v12, v12, v13
	s_waitcnt lgkmcnt(1)
	v_sub_f32_e32 v9, v23, v226
	v_min_f32_e32 v9, 0x42e6d4ca, v9
	s_nop 0
	v_exp_f32_e32 v16, v9
	v_sub_f32_e32 v9, v22, v227
	v_min_f32_e32 v9, 0x42e6d4ca, v9
	s_nop 0
	v_exp_f32_e32 v17, v9
	s_waitcnt lgkmcnt(0)
	v_pk_mul_f32 v[16:17], v[228:229], v[16:17]
	s_nop 0
	v_cvt_pk_bf16_f32 v13, v16, v17
	s_nop 1
	v_mfma_f32_16x16x32_bf16 v[16:19], v[10:13], v[0:3], 0
	s_and_saveexec_b64 s[2:3], vcc
	s_cbranch_execz .LBB0_221
	v_cmp_gt_u32_e32 vcc, v24, v107
	s_nop 4
	v_cndmask_b32_e32 v9, v18, v18, vcc
	v_cndmask_b32_e32 v10, v19, v19, vcc
	v_cndmask_b32_e64 v11, v16, 0, vcc
	v_cmp_lt_u32_e32 vcc, v24, v107
	s_nop 1
	v_cndmask_b32_e32 v16, v11, v16, vcc
	v_cndmask_b32_e32 v10, v10, v19, vcc
	v_cndmask_b32_e32 v9, v9, v18, vcc
	v_cndmask_b32_e32 v17, 0, v17, vcc
	v_cmp_le_u32_e32 vcc, v31, v107
	s_nop 1
	v_cndmask_b32_e32 v18, 0, v9, vcc
	v_cmp_le_u32_e32 vcc, v30, v107
	s_nop 1
	v_cndmask_b32_e32 v19, 0, v10, vcc

.LBB0_222:
	s_or_b64 exec, exec, s[4:5]
	v_cmp_lt_u32_e32 vcc, 1, v108
	v_mov_b32_e32 v9, 0
	v_mov_b32_e32 v10, 0
	v_mov_b32_e32 v11, 0
	s_and_saveexec_b64 s[4:5], vcc
	s_cbranch_execz .LBB0_226
	v_add_u32_e32 v8, 0x1080, v29
	ds_read2_b32 v[200:201], v8 offset1:1
	v_add_u32_e32 v253, 0x5480, v29
	ds_read2_b32 v[202:203], v253 offset1:1
	v_add_u32_e32 v252, 0x1088, v29
	ds_read2_b32 v[204:205], v252 offset1:1
	v_add_u32_e32 v251, 0x5488, v29
	ds_read2_b32 v[220:221], v251 offset1:1
	v_add_u32_e32 v250, 0x1090, v29
	ds_read2_b32 v[222:223], v250 offset1:1
	v_add_u32_e32 v249, 0x5490, v29
	ds_read2_b32 v[224:225], v249 offset1:1
	v_add_u32_e32 v248, 0x1098, v29
	ds_read2_b32 v[226:227], v248 offset1:1
	v_add_u32_e32 v247, 0x5498, v29
	ds_read2_b32 v[228:229], v247 offset1:1
	v_cmp_eq_u32_e64 s[36:37], 2, v108
	s_waitcnt lgkmcnt(1)
	v_sub_f32_e32 v8, v26, v200
	v_sub_f32_e32 v9, v25, v201
	v_min_f32_e32 v8, 0x42e6d4ca, v8
	v_min_f32_e32 v9, 0x42e6d4ca, v9
	s_nop 0
	s_nop 0
	v_exp_f32_e32 v8, v8
	v_exp_f32_e32 v9, v9
	s_waitcnt lgkmcnt(0)
	v_pk_mul_f32 v[8:9], v[202:203], v[8:9]
	s_nop 0
	v_cvt_pk_bf16_f32 v8, v8, v9
	s_waitcnt lgkmcnt(0)
	v_sub_f32_e32 v9, v28, v204
	v_min_f32_e32 v9, 0x42e6d4ca, v9
	s_nop 0
	v_exp_f32_e32 v10, v9
	v_sub_f32_e32 v9, v27, v205
	v_min_f32_e32 v9, 0x42e6d4ca, v9
	s_nop 0
	v_exp_f32_e32 v11, v9
	s_waitcnt lgkmcnt(0)
	v_pk_mul_f32 v[10:11], v[220:221], v[10:11]
	s_nop 0
	v_cvt_pk_bf16_f32 v9, v10, v11
	s_waitcnt lgkmcnt(1)
	v_sub_f32_e32 v10, v21, v222
	v_sub_f32_e32 v11, v20, v223
	v_min_f32_e32 v10, 0x42e6d4ca, v10
	v_min_f32_e32 v11, 0x42e6d4ca, v11
	s_nop 0
	s_nop 0
	v_exp_f32_e32 v10, v10
	v_exp_f32_e32 v11, v11
	s_waitcnt lgkmcnt(0)
	v_pk_mul_f32 v[10:11], v[224:225], v[10:11]
	s_nop 0
	v_cvt_pk_bf16_f32 v10, v10, v11
	s_waitcnt lgkmcnt(0)
	v_sub_f32_e32 v11, v23, v226
	v_min_f32_e32 v11, 0x42e6d4ca, v11
	s_nop 0
	v_exp_f32_e32 v12, v11
	v_sub_f32_e32 v11, v22, v227
	v_min_f32_e32 v11, 0x42e6d4ca, v11
	s_nop 0
	v_exp_f32_e32 v13, v11
	s_waitcnt lgkmcnt(0)
	v_pk_mul_f32 v[12:13], v[228:229], v[12:13]
	s_nop 0
	v_cvt_pk_bf16_f32 v11, v12, v13
	s_nop 1
	v_mfma_f32_16x16x32_bf16 v[8:11], v[8:11], v[0:3], 0
	s_waitcnt lgkmcnt(0)
	v_mov_b32_e32 v32, v228
	v_mov_b32_e32 v33, v229
	s_and_saveexec_b64 s[2:3], s[36:37]
	s_cbranch_execz .LBB0_225
	v_cmp_gt_u32_e64 s[36:37], v24, v107
	s_nop 4
	v_cndmask_b32_e64 v12, v10, v10, s[36:37]
	v_cndmask_b32_e64 v13, v11, v11, s[36:37]
	v_cndmask_b32_e64 v14, v8, 0, s[36:37]
	v_cmp_lt_u32_e64 s[36:37], v24, v107
	s_nop 1
	v_cndmask_b32_e64 v8, v14, v8, s[36:37]
	v_cndmask_b32_e64 v11, v13, v11, s[36:37]
	v_cndmask_b32_e64 v10, v12, v10, s[36:37]
	v_cndmask_b32_e64 v9, 0, v9, s[36:37]
	v_cmp_le_u32_e64 s[36:37], v31, v107
	s_nop 1
	v_cndmask_b32_e64 v10, 0, v10, s[36:37]
	v_cmp_le_u32_e64 s[36:37], v30, v107
	s_nop 1
	v_cndmask_b32_e64 v11, 0, v11, s[36:37]

.LBB0_226:
	s_or_b64 exec, exec, s[4:5]
	v_cmp_eq_u32_e64 s[36:37], 3, v108
	v_mov_b32_e32 v12, 0
	v_mov_b32_e32 v13, 0
	v_mov_b32_e32 v14, 0
	v_mov_b32_e32 v32, 0
	s_and_saveexec_b64 s[4:5], s[36:37]
	s_cbranch_execz .LBB0_228
	v_add_u32_e32 v12, 0x18c0, v29
	v_add_u32_e32 v32, 0x18c8, v29
	v_add_u32_e32 v34, 0x5cc8, v29
	v_add_u32_e32 v14, 0x5cc0, v29
	ds_read2_b32 v[200:201], v12 offset1:1
	ds_read2_b32 v[202:203], v32 offset1:1
	ds_read2_b32 v[204:205], v34 offset1:1
	ds_read2_b32 v[220:221], v14 offset1:1
	v_add_u32_e32 v253, 0x18d0, v29
	ds_read2_b32 v[222:223], v253 offset1:1
	v_add_u32_e32 v252, 0x5cd0, v29
	ds_read2_b32 v[224:225], v252 offset1:1
	v_add_u32_e32 v251, 0x18d8, v29
	ds_read2_b32 v[226:227], v251 offset1:1
	v_add_u32_e32 v250, 0x5cd8, v29
	ds_read2_b32 v[228:229], v250 offset1:1
	v_cmp_lt_u32_e64 s[36:37], v24, v107
	s_waitcnt lgkmcnt(2)
	v_sub_f32_e32 v14, v28, v202
	v_min_f32_e32 v14, 0x42e6d4ca, v14
	v_sub_f32_e32 v12, v26, v200
	v_sub_f32_e32 v13, v25, v201
	s_nop 0
	v_min_f32_e32 v12, 0x42e6d4ca, v12
	v_min_f32_e32 v13, 0x42e6d4ca, v13
	v_exp_f32_e32 v32, v14
	v_sub_f32_e32 v14, v27, v203
	s_nop 0
	s_nop 0
	v_min_f32_e32 v14, 0x42e6d4ca, v14
	v_exp_f32_e32 v12, v12
	v_exp_f32_e32 v13, v13
	s_nop 0
	v_exp_f32_e32 v33, v14
	s_waitcnt lgkmcnt(0)
	v_pk_mul_f32 v[12:13], v[220:221], v[12:13]
	v_cvt_pk_bf16_f32 v26, v12, v13
	v_pk_mul_f32 v[12:13], v[204:205], v[32:33]
	v_cvt_pk_bf16_f32 v27, v12, v13
	s_waitcnt lgkmcnt(3)
	v_sub_f32_e32 v14, v21, v222
	v_min_f32_e32 v14, 0x42e6d4ca, v14
	s_nop 0
	v_exp_f32_e32 v32, v14
	v_sub_f32_e32 v14, v20, v223
	v_min_f32_e32 v14, 0x42e6d4ca, v14
	s_nop 0
	v_exp_f32_e32 v33, v14
	s_waitcnt lgkmcnt(1)
	v_sub_f32_e32 v14, v23, v226
	v_min_f32_e32 v14, 0x42e6d4ca, v14
	s_nop 0
	v_exp_f32_e32 v20, v14
	v_sub_f32_e32 v14, v22, v227
	v_min_f32_e32 v14, 0x42e6d4ca, v14
	s_nop 0
	v_exp_f32_e32 v21, v14
	v_pk_mul_f32 v[12:13], v[224:225], v[32:33]
	s_nop 0
	v_cvt_pk_bf16_f32 v28, v12, v13
	s_waitcnt lgkmcnt(0)
	v_pk_mul_f32 v[12:13], v[228:229], v[20:21]
	s_nop 0
	v_cvt_pk_bf16_f32 v29, v12, v13
	s_nop 1
	v_mfma_f32_16x16x32_bf16 v[0:3], v[26:29], v[0:3], 0
	s_nop 7
	v_cndmask_b32_e64 v13, 0, v1, s[36:37]
	v_cmp_le_u32_e64 s[36:37], v24, v107
	s_nop 1
	v_cndmask_b32_e64 v12, 0, v0, s[36:37]
	v_cmp_le_u32_e64 s[36:37], v31, v107
	s_nop 1
	v_cndmask_b32_e64 v14, 0, v2, s[36:37]
	v_cmp_le_u32_e64 s[36:37], v30, v107
	s_nop 1
	v_cndmask_b32_e64 v32, 0, v3, s[36:37]
	s_waitcnt lgkmcnt(0)
	v_mov_b32_e32 v34, v226
	v_mov_b32_e32 v35, v227
	v_mov_b32_e32 v36, v228
	v_mov_b32_e32 v37, v229

.LBB0_234:
	s_mov_b32 s100, 0x42ad1f97
	v_sub_f32_e32 v220, 1.0, v36
	v_lshlrev_b32_e32 v40, 16, v40
	v_lshlrev_b32_e32 v51, 16, v51
	v_lshlrev_b32_e32 v50, 16, v50
	v_lshlrev_b32_e32 v49, 16, v49
	v_mul_f32_e32 v190, 0x3fb8aa3b, v40
	v_mul_f32_e32 v195, 0x3fb8aa3b, v51
	v_mul_f32_e32 v200, 0x3fb8aa3b, v50
	v_mul_f32_e32 v205, 0x3fb8aa3b, v49
	v_min_f32_e64 v186, -v190, s100
	v_min_f32_e64 v191, -v195, s100
	v_min_f32_e64 v196, -v200, s100
	v_min_f32_e64 v201, -v205, s100
	v_exp_f32_e32 v186, v186
	v_exp_f32_e32 v191, v191
	v_exp_f32_e32 v196, v196
	v_exp_f32_e32 v201, v201
	v_add_f32_e32 v187, 1.0, v186
	v_add_f32_e32 v192, 1.0, v191
	v_add_f32_e32 v197, 1.0, v196
	v_add_f32_e32 v202, 1.0, v201
	v_fma_f32 v189, v186, v36, 1.0
	v_fma_f32 v194, v191, v36, 1.0
	v_fma_f32 v199, v196, v36, 1.0
	v_fma_f32 v204, v201, v36, 1.0
	v_rcp_f32_e32 v188, v187
	v_rcp_f32_e32 v193, v192
	v_rcp_f32_e32 v198, v197
	v_rcp_f32_e32 v203, v202
	v_log_f32_e32 v187, v187
	v_log_f32_e32 v192, v192
	v_log_f32_e32 v197, v197
	v_log_f32_e32 v202, v202
	v_log_f32_e32 v189, v189
	v_log_f32_e32 v194, v194
	v_log_f32_e32 v199, v199
	v_log_f32_e32 v204, v204
	v_mul_f32_e32 v188, v186, v188
	v_mul_f32_e32 v193, v191, v193
	v_mul_f32_e32 v198, v196, v198
	v_mul_f32_e32 v203, v201, v203
	v_min_f32_e64 v187, v190, -v187
	v_min_f32_e64 v192, v195, -v192
	v_min_f32_e64 v197, v200, -v197
	v_min_f32_e64 v202, v205, -v202
	v_mul_f32_e32 v144, v188, v220
	v_mul_f32_e32 v145, v193, v220
	v_mul_f32_e32 v146, v198, v220
	v_mul_f32_e32 v147, v203, v220
	v_add_f32_e32 v187, v187, v189
	v_add_f32_e32 v192, v192, v194
	v_add_f32_e32 v197, v197, v199
	v_add_f32_e32 v202, v202, v204
	v_add_f32_e32 v128, 0, v187
	v_add_f32_e32 v129, v192, v128
	v_add_f32_e32 v130, v197, v129
	v_add_f32_e32 v131, v202, v130
	v_lshlrev_b32_e32 v48, 16, v48
	v_lshlrev_b32_e32 v47, 16, v47
	v_lshlrev_b32_e32 v46, 16, v46
	v_lshlrev_b32_e32 v45, 16, v45
	v_mul_f32_e32 v190, 0x3fb8aa3b, v48
	v_mul_f32_e32 v195, 0x3fb8aa3b, v47
	v_mul_f32_e32 v200, 0x3fb8aa3b, v46
	v_mul_f32_e32 v205, 0x3fb8aa3b, v45
	v_min_f32_e64 v186, -v190, s100
	v_min_f32_e64 v191, -v195, s100
	v_min_f32_e64 v196, -v200, s100
	v_min_f32_e64 v201, -v205, s100
	v_exp_f32_e32 v186, v186
	v_exp_f32_e32 v191, v191
	v_exp_f32_e32 v196, v196
	v_exp_f32_e32 v201, v201
	v_add_f32_e32 v187, 1.0, v186
	v_add_f32_e32 v192, 1.0, v191
	v_add_f32_e32 v197, 1.0, v196
	v_add_f32_e32 v202, 1.0, v201
	v_fma_f32 v189, v186, v36, 1.0
	v_fma_f32 v194, v191, v36, 1.0
	v_fma_f32 v199, v196, v36, 1.0
	v_fma_f32 v204, v201, v36, 1.0
	v_rcp_f32_e32 v188, v187
	v_rcp_f32_e32 v193, v192
	v_rcp_f32_e32 v198, v197
	v_rcp_f32_e32 v203, v202
	v_log_f32_e32 v187, v187
	v_log_f32_e32 v192, v192
	v_log_f32_e32 v197, v197
	v_log_f32_e32 v202, v202
	v_log_f32_e32 v189, v189
	v_log_f32_e32 v194, v194
	v_log_f32_e32 v199, v199
	v_log_f32_e32 v204, v204
	v_mul_f32_e32 v188, v186, v188
	v_mul_f32_e32 v193, v191, v193
	v_mul_f32_e32 v198, v196, v198
	v_mul_f32_e32 v203, v201, v203
	v_min_f32_e64 v187, v190, -v187
	v_min_f32_e64 v192, v195, -v192
	v_min_f32_e64 v197, v200, -v197
	v_min_f32_e64 v202, v205, -v202
	v_mul_f32_e32 v148, v188, v220
	v_mul_f32_e32 v149, v193, v220
	v_mul_f32_e32 v150, v198, v220
	v_mul_f32_e32 v151, v203, v220
	v_add_f32_e32 v187, v187, v189
	v_add_f32_e32 v192, v192, v194
	v_add_f32_e32 v197, v197, v199
	v_add_f32_e32 v202, v202, v204
	v_add_f32_e32 v132, v187, v131
	v_add_f32_e32 v133, v192, v132
	v_add_f32_e32 v134, v197, v133
	v_add_f32_e32 v135, v202, v134
	v_lshlrev_b32_e32 v44, 16, v44
	v_lshlrev_b32_e32 v43, 16, v43
	v_lshlrev_b32_e32 v42, 16, v42
	v_lshlrev_b32_e32 v41, 16, v41
	v_mul_f32_e32 v190, 0x3fb8aa3b, v44
	v_mul_f32_e32 v195, 0x3fb8aa3b, v43
	v_mul_f32_e32 v200, 0x3fb8aa3b, v42
	v_mul_f32_e32 v205, 0x3fb8aa3b, v41
	v_min_f32_e64 v186, -v190, s100
	v_min_f32_e64 v191, -v195, s100
	v_min_f32_e64 v196, -v200, s100
	v_min_f32_e64 v201, -v205, s100
	v_exp_f32_e32 v186, v186
	v_exp_f32_e32 v191, v191
	v_exp_f32_e32 v196, v196
	v_exp_f32_e32 v201, v201
	v_add_f32_e32 v187, 1.0, v186
	v_add_f32_e32 v192, 1.0, v191
	v_add_f32_e32 v197, 1.0, v196
	v_add_f32_e32 v202, 1.0, v201
	v_fma_f32 v189, v186, v36, 1.0
	v_fma_f32 v194, v191, v36, 1.0
	v_fma_f32 v199, v196, v36, 1.0
	v_fma_f32 v204, v201, v36, 1.0
	v_rcp_f32_e32 v188, v187
	v_rcp_f32_e32 v193, v192
	v_rcp_f32_e32 v198, v197
	v_rcp_f32_e32 v203, v202
	v_log_f32_e32 v187, v187
	v_log_f32_e32 v192, v192
	v_log_f32_e32 v197, v197
	v_log_f32_e32 v202, v202
	v_log_f32_e32 v189, v189
	v_log_f32_e32 v194, v194
	v_log_f32_e32 v199, v199
	v_log_f32_e32 v204, v204
	v_mul_f32_e32 v188, v186, v188
	v_mul_f32_e32 v193, v191, v193
	v_mul_f32_e32 v198, v196, v198
	v_mul_f32_e32 v203, v201, v203
	v_min_f32_e64 v187, v190, -v187
	v_min_f32_e64 v192, v195, -v192
	v_min_f32_e64 v197, v200, -v197
	v_min_f32_e64 v202, v205, -v202
	v_mul_f32_e32 v152, v188, v220
	v_mul_f32_e32 v153, v193, v220
	v_mul_f32_e32 v154, v198, v220
	v_mul_f32_e32 v155, v203, v220
	v_add_f32_e32 v187, v187, v189
	v_add_f32_e32 v192, v192, v194
	v_add_f32_e32 v197, v197, v199
	v_add_f32_e32 v202, v202, v204
	v_add_f32_e32 v136, v187, v135
	v_add_f32_e32 v137, v192, v136
	v_add_f32_e32 v138, v197, v137
	v_add_f32_e32 v139, v202, v138
	v_lshlrev_b32_e32 v39, 16, v39
	v_lshlrev_b32_e32 v38, 16, v38
	v_lshlrev_b32_e32 v37, 16, v37
	v_lshlrev_b32_e32 v35, 16, v35
	v_mul_f32_e32 v190, 0x3fb8aa3b, v39
	v_mul_f32_e32 v195, 0x3fb8aa3b, v38
	v_mul_f32_e32 v200, 0x3fb8aa3b, v37
	v_mul_f32_e32 v205, 0x3fb8aa3b, v35
	v_min_f32_e64 v186, -v190, s100
	v_min_f32_e64 v191, -v195, s100
	v_min_f32_e64 v196, -v200, s100
	v_min_f32_e64 v201, -v205, s100
	v_exp_f32_e32 v186, v186
	v_exp_f32_e32 v191, v191
	v_exp_f32_e32 v196, v196
	v_exp_f32_e32 v201, v201
	v_add_f32_e32 v187, 1.0, v186
	v_add_f32_e32 v192, 1.0, v191
	v_add_f32_e32 v197, 1.0, v196
	v_add_f32_e32 v202, 1.0, v201
	v_fma_f32 v189, v186, v36, 1.0
	v_fma_f32 v194, v191, v36, 1.0
	v_fma_f32 v199, v196, v36, 1.0
	v_fma_f32 v204, v201, v36, 1.0
	v_rcp_f32_e32 v188, v187
	v_rcp_f32_e32 v193, v192
	v_rcp_f32_e32 v198, v197
	v_rcp_f32_e32 v203, v202
	v_log_f32_e32 v187, v187
	v_log_f32_e32 v192, v192
	v_log_f32_e32 v197, v197
	v_log_f32_e32 v202, v202
	v_log_f32_e32 v189, v189
	v_log_f32_e32 v194, v194
	v_log_f32_e32 v199, v199
	v_log_f32_e32 v204, v204
	v_mul_f32_e32 v188, v186, v188
	v_mul_f32_e32 v193, v191, v193
	v_mul_f32_e32 v198, v196, v198
	v_mul_f32_e32 v203, v201, v203
	v_min_f32_e64 v187, v190, -v187
	v_min_f32_e64 v192, v195, -v192
	v_min_f32_e64 v197, v200, -v197
	v_min_f32_e64 v202, v205, -v202
	v_mul_f32_e32 v156, v188, v220
	v_mul_f32_e32 v157, v193, v220
	v_mul_f32_e32 v158, v198, v220
	v_mul_f32_e32 v159, v203, v220
	v_add_f32_e32 v187, v187, v189
	v_add_f32_e32 v192, v192, v194
	v_add_f32_e32 v197, v197, v199
	v_add_f32_e32 v202, v202, v204
	v_add_f32_e32 v140, v187, v139
	v_add_f32_e32 v141, v192, v140
	v_add_f32_e32 v142, v197, v141
	v_add_f32_e32 v143, v202, v142
	s_mov_b32 s3, 0xbfb8aa3b
	v_lshrrev_b32_e32 v28, 8, v28
	s_movk_i32 s2, 0x410
	v_mul_i32_i24_e32 v28, 0xd800, v28
	v_mad_u32_u24 v40, v29, s2, v21
	v_lshl_add_u32 v40, v40, 2, v28
	v_mov_b32_e32 v160, v40
	v_add_u32_e32 v52, 0x4400, v40
	v_and_b32_e32 v33, 0xff, v33
	v_mul_u32_u24_e32 v31, 0x48, v31
	v_add_u32_e32 v51, 0x400, v40
	v_add_u32_e32 v49, 0x4800, v40
	v_lshlrev_b32_e32 v31, 1, v31
	v_lshlrev_b32_e32 v30, 1, v30
	v_cmp_lt_u32_e32 vcc, 63, v33
	s_nop 0
	v_add_u32_e32 v47, 0x800, v40
	v_add_u32_e32 v45, 0x4c00, v40
	s_nop 0
	s_nop 0
	v_add_u32_e32 v43, 0xc00, v40
	v_add_u32_e32 v40, 0x5000, v40
	v_lshl_add_u32 v34, v33, 2, v28
	v_add_u32_e32 v161, 0x400, v160
	v_add_u32_e32 v162, 0x800, v160
	v_add_u32_e32 v163, 0xc00, v160
	v_add_u32_e32 v164, 0x4400, v160
	v_add_u32_e32 v165, 0x4800, v160
	v_add_u32_e32 v166, 0x4c00, v160
	v_add_u32_e32 v167, 0x5000, v160
	ds_write2_b32 v160, v128, v129 offset1:65
	ds_write2_b32 v164, v144, v145 offset1:65
	ds_write2_b32 v160, v130, v131 offset0:130 offset1:195
	ds_write2_b32 v164, v146, v147 offset0:130 offset1:195
	ds_write2_b32 v161, v132, v133 offset0:4 offset1:69
	ds_write2_b32 v165, v148, v149 offset0:4 offset1:69
	ds_write2_b32 v161, v134, v135 offset0:134 offset1:199
	ds_write2_b32 v165, v150, v151 offset0:134 offset1:199
	ds_write2_b32 v162, v136, v137 offset0:8 offset1:73
	ds_write2_b32 v166, v152, v153 offset0:8 offset1:73
	ds_write2_b32 v162, v138, v139 offset0:138 offset1:203
	ds_write2_b32 v166, v154, v155 offset0:138 offset1:203
	ds_write2_b32 v167, v156, v157 offset0:12 offset1:77
	ds_write2_b32 v163, v140, v141 offset0:12 offset1:77
	ds_write2_b32 v163, v142, v143 offset0:142 offset1:207
	ds_write2_b32 v167, v158, v159 offset0:142 offset1:207
	ds_write_b32 v34, v143 offset:53248
	v_add3_u32 v34, v28, v31, v30
	v_add3_u32 v30, v28, v30, v31
	ds_write_b16 v34, v12 offset:34816
	ds_write_b16_d16_hi v30, v12 offset:34960
	ds_write_b16 v34, v13 offset:35104
	ds_write_b16_d16_hi v30, v13 offset:35248
	ds_write_b16 v34, v14 offset:35392
	ds_write_b16_d16_hi v30, v14 offset:35536
	ds_write_b16 v34, v15 offset:35680
	ds_write_b16_d16_hi v30, v15 offset:35824
	ds_write_b16 v34, v8 offset:35968
	ds_write_b16_d16_hi v30, v8 offset:36112
	ds_write_b16 v34, v9 offset:36256
	ds_write_b16_d16_hi v30, v9 offset:36400
	ds_write_b16 v34, v10 offset:36544
	ds_write_b16_d16_hi v30, v10 offset:36688
	ds_write_b16 v34, v11 offset:36832
	ds_write_b16_d16_hi v30, v11 offset:36976
	s_waitcnt lgkmcnt(0)
	s_barrier
	s_and_saveexec_b64 s[2:3], vcc
	s_cbranch_execz .LBB0_238
	v_lshlrev_b32_e32 v8, 2, v21
	s_mov_b32 s4, 0xd000
	v_add3_u32 v8, v28, v8, s4
	v_mov_b32_e32 v20, 0
	s_mov_b64 s[4:5], 0

.LBB0_238:
	s_or_b64 exec, exec, s[2:3]
	v_lshlrev_b32_e32 v29, 3, v23
	v_lshl_add_u32 v8, v21, 2, v28
	v_mov_b32_e32 v21, v20
	v_mad_u32_u24 v30, v18, s14, v8
	ds_read_b32 v80, v30
	ds_read_b32 v81, v30 offset:260
	ds_read_b32 v82, v30 offset:520
	ds_read_b32 v83, v30 offset:780
	ds_read_b32 v84, v30 offset:1040
	ds_read_b32 v85, v30 offset:1300
	ds_read_b32 v86, v30 offset:1560
	ds_read_b32 v87, v30 offset:1820
	ds_read_b32 v88, v30 offset:2080
	ds_read_b32 v89, v30 offset:2340
	ds_read_b32 v90, v30 offset:2600
	ds_read_b32 v91, v30 offset:2860
	ds_read_b32 v92, v30 offset:3120
	ds_read_b32 v93, v30 offset:3380
	ds_read_b32 v94, v30 offset:3640
	ds_read_b32 v95, v30 offset:3900
	s_waitcnt lgkmcnt(0)
	v_add_f32_e32 v80, v20, v80
	v_add_f32_e32 v81, v20, v81
	v_add_f32_e32 v82, v20, v82
	v_add_f32_e32 v83, v20, v83
	v_add_f32_e32 v84, v20, v84
	v_add_f32_e32 v85, v20, v85
	v_add_f32_e32 v86, v20, v86
	v_add_f32_e32 v87, v20, v87
	v_add_f32_e32 v88, v20, v88
	v_add_f32_e32 v89, v20, v89
	v_add_f32_e32 v90, v20, v90
	v_add_f32_e32 v91, v20, v91
	v_add_f32_e32 v92, v20, v92
	v_add_f32_e32 v93, v20, v93
	v_add_f32_e32 v94, v20, v94
	v_add_f32_e32 v95, v20, v95
	ds_write_b32 v30, v80
	ds_write_b32 v30, v81 offset:260
	ds_write_b32 v30, v82 offset:520
	ds_write_b32 v30, v83 offset:780
	ds_write_b32 v30, v84 offset:1040
	ds_write_b32 v30, v85 offset:1300
	ds_write_b32 v30, v86 offset:1560
	ds_write_b32 v30, v87 offset:1820
	ds_write_b32 v30, v88 offset:2080
	ds_write_b32 v30, v89 offset:2340
	ds_write_b32 v30, v90 offset:2600
	ds_write_b32 v30, v91 offset:2860
	ds_write_b32 v30, v92 offset:3120
	ds_write_b32 v30, v93 offset:3380
	ds_write_b32 v30, v94 offset:3640
	ds_write_b32 v30, v95 offset:3900
	v_and_b32_e32 v9, 63, v22
	v_lshlrev_b32_e32 v10, 2, v9
	v_add_u32_e32 v8, v28, v10
	s_waitcnt lgkmcnt(0)
	s_barrier
	ds_read_b32 v8, v8 offset:16380
	s_movk_i32 s2, 0x90
	v_mad_u32_u24 v9, v9, s2, v28
	v_lshlrev_b32_e32 v11, 5, v17
	s_mov_b32 s2, 0xac00
	v_add3_u32 v9, v9, v11, s2
	v_mul_u32_u24_e32 v11, 0x1040, v17
	v_add3_u32 v10, v28, v11, v10
	v_add_u32_e32 v72, 0x410, v10
	v_add_u32_e32 v73, 0x820, v10
	v_add_u32_e32 v74, 0xc30, v10
	v_add_u32_e32 v76, 0x4400, v10
	v_add_u32_e32 v77, 0x4810, v10
	v_add_u32_e32 v78, 0x4c20, v10
	v_add_u32_e32 v79, 0x5030, v10
	ds_read2_b32 v[96:97], v76 offset1:65
	ds_read2_b32 v[98:99], v10 offset1:65
	ds_read2_b32 v[100:101], v76 offset0:130 offset1:195
	ds_read2_b32 v[102:103], v10 offset0:130 offset1:195
	ds_read2_b32 v[104:105], v77 offset1:65
	ds_read2_b32 v[106:107], v72 offset1:65
	ds_read2_b32 v[108:109], v77 offset0:130 offset1:195
	ds_read2_b32 v[110:111], v72 offset0:130 offset1:195
	ds_read2_b32 v[112:113], v78 offset1:65
	ds_read2_b32 v[114:115], v73 offset1:65
	ds_read2_b32 v[116:117], v78 offset0:130 offset1:195
	ds_read2_b32 v[118:119], v73 offset0:130 offset1:195
	ds_read2_b32 v[120:121], v79 offset1:65
	ds_read2_b32 v[122:123], v74 offset1:65
	ds_read2_b32 v[124:125], v79 offset0:130 offset1:195
	ds_read2_b32 v[126:127], v74 offset0:130 offset1:195
	s_waitcnt lgkmcnt(0)
	v_sub_f32_e32 v98, v8, v98
	v_sub_f32_e32 v99, v8, v99
	v_sub_f32_e32 v102, v8, v102
	v_sub_f32_e32 v103, v8, v103
	s_nop 0
	s_nop 0
	s_nop 0
	s_nop 0
	v_exp_f32_e32 v98, v98
	v_exp_f32_e32 v99, v99
	v_exp_f32_e32 v102, v102
	v_exp_f32_e32 v103, v103
	s_nop 0
	v_mul_f32_e32 v98, v96, v98
	v_mul_f32_e32 v99, v97, v99
	v_mul_f32_e32 v102, v100, v102
	v_mul_f32_e32 v103, v101, v103
	v_cvt_pk_bf16_f32 v96, v98, v99
	v_cvt_pk_bf16_f32 v97, v102, v103
	ds_write_b64 v9, v[96:97]
	v_sub_f32_e32 v106, v8, v106
	v_sub_f32_e32 v107, v8, v107
	v_sub_f32_e32 v110, v8, v110
	v_sub_f32_e32 v111, v8, v111
	s_nop 0
	s_nop 0
	s_nop 0
	s_nop 0
	v_exp_f32_e32 v106, v106
	v_exp_f32_e32 v107, v107
	v_exp_f32_e32 v110, v110
	v_exp_f32_e32 v111, v111
	s_nop 0
	v_mul_f32_e32 v106, v104, v106
	v_mul_f32_e32 v107, v105, v107
	v_mul_f32_e32 v110, v108, v110
	v_mul_f32_e32 v111, v109, v111
	v_cvt_pk_bf16_f32 v104, v106, v107
	v_cvt_pk_bf16_f32 v105, v110, v111
	ds_write_b64 v9, v[104:105] offset:8
	v_sub_f32_e32 v114, v8, v114
	v_sub_f32_e32 v115, v8, v115
	v_sub_f32_e32 v118, v8, v118
	v_sub_f32_e32 v119, v8, v119
	s_nop 0
	s_nop 0
	s_nop 0
	s_nop 0
	v_exp_f32_e32 v114, v114
	v_exp_f32_e32 v115, v115
	v_exp_f32_e32 v118, v118
	v_exp_f32_e32 v119, v119
	s_nop 0
	v_mul_f32_e32 v114, v112, v114
	v_mul_f32_e32 v115, v113, v115
	v_mul_f32_e32 v118, v116, v118
	v_mul_f32_e32 v119, v117, v119
	v_cvt_pk_bf16_f32 v112, v114, v115
	v_cvt_pk_bf16_f32 v113, v118, v119
	ds_write_b64 v9, v[112:113] offset:16
	v_sub_f32_e32 v122, v8, v122
	v_sub_f32_e32 v123, v8, v123
	v_sub_f32_e32 v126, v8, v126
	v_sub_f32_e32 v127, v8, v127
	s_nop 0
	s_nop 0
	s_nop 0
	s_nop 0
	v_exp_f32_e32 v122, v122
	v_exp_f32_e32 v123, v123
	v_exp_f32_e32 v126, v126
	v_exp_f32_e32 v127, v127
	s_nop 0
	v_mul_f32_e32 v122, v120, v122
	v_mul_f32_e32 v123, v121, v123
	v_mul_f32_e32 v126, v124, v126
	v_mul_f32_e32 v127, v125, v127
	v_cvt_pk_bf16_f32 v120, v122, v123
	v_cvt_pk_bf16_f32 v121, v126, v127
	ds_write_b64 v9, v[120:121] offset:24
	v_lshl_add_u32 v12, v29, 1, v28
	s_movk_i32 s2, 0x90
	v_mad_u32_u24 v17, v19, s2, v12
	s_waitcnt lgkmcnt(0)
	s_barrier
	ds_read_b128 v[8:11], v17 offset:34816
	v_mad_u32_u24 v18, v26, s2, v12
	ds_read_b128 v[12:15], v18 offset:44032
	ds_read_b128 v[34:37], v18 offset:46336
	ds_read_b128 v[38:41], v18 offset:48640
	ds_read_b128 v[42:45], v18 offset:50944
	s_waitcnt lgkmcnt(3)
	v_mfma_f32_16x16x32_bf16 v[12:15], v[12:15], v[8:11], 0
	v_lshlrev_b32_e32 v30, 2, v23
	v_mov_b32_e32 v33, v177
	v_or_b32_e32 v51, 16, v26
	s_waitcnt lgkmcnt(2)
	v_mfma_f32_16x16x32_bf16 v[34:37], v[34:37], v[8:11], 0
	v_or_b32_e32 v48, 32, v26
	v_or_b32_e32 v31, 48, v26
	v_cmp_lt_u32_sdwa s[4:5], v22, v216 src0_sel:BYTE_0 src1_sel:DWORD
	s_waitcnt lgkmcnt(1)
	v_mfma_f32_16x16x32_bf16 v[38:41], v[38:41], v[8:11], 0
	s_waitcnt lgkmcnt(0)
	v_mfma_f32_16x16x32_bf16 v[8:11], v[42:45], v[8:11], 0
	ds_read_b128 v[42:45], v17 offset:34880
	ds_read_b128 v[52:55], v18 offset:44096
	v_ashrrev_i32_e32 v17, 31, v16
	v_lshlrev_b64 v[20:21], 14, v[16:17]
	s_waitcnt lgkmcnt(0)
	v_mfma_f32_16x16x32_bf16 v[12:15], v[52:55], v[42:45], v[12:15]
	ds_read_b128 v[52:55], v18 offset:46400
	v_lshl_add_u64 v[20:21], s[78:79], 0, v[20:21]
	s_waitcnt lgkmcnt(0)
	v_mfma_f32_16x16x32_bf16 v[34:37], v[52:55], v[42:45], v[34:37]
	ds_read_b128 v[52:55], v18 offset:48704
	s_waitcnt lgkmcnt(0)
	v_mfma_f32_16x16x32_bf16 v[38:41], v[52:55], v[42:45], v[38:41]
	ds_read_b128 v[52:55], v18 offset:51008
	v_or_b32_e32 v66, v32, v26
	v_lshl_or_b32 v66, v66, 6, v30
	v_lshlrev_b32_e32 v66, 2, v66
	v_mov_b32_e32 v67, v177
	v_lshl_add_u64 v[66:67], v[20:21], 0, v[66:67]
	v_or_b32_e32 v18, v32, v30
	v_lshlrev_b32_e32 v18, 6, v18
	v_or_b32_e32 v23, v18, v26
	v_lshlrev_b32_e32 v32, 2, v23
	v_lshl_add_u64 v[32:33], v[20:21], 0, v[32:33]
	global_store_dwordx4 v[66:67], v[12:15], off sc1
	global_store_dwordx4 v[66:67], v[34:37], off offset:64 sc1
	global_store_dwordx4 v[66:67], v[38:41], off offset:128 sc1
	s_nop 1
	v_or_b32_e32 v12, v18, v51
	v_lshlrev_b32_e32 v12, 2, v12
	v_mov_b32_e32 v13, v177
	v_lshl_add_u64 v[12:13], v[20:21], 0, v[12:13]
	v_or_b32_e32 v12, v18, v48
	v_lshlrev_b32_e32 v12, 2, v12
	v_mov_b32_e32 v13, v177
	s_waitcnt lgkmcnt(0)
	v_mfma_f32_16x16x32_bf16 v[8:11], v[52:55], v[42:45], v[8:11]
	v_lshl_add_u64 v[12:13], v[20:21], 0, v[12:13]
	s_nop 3
	s_nop 3
	global_store_dwordx4 v[66:67], v[8:11], off offset:192 sc1
	s_nop 1
	v_or_b32_e32 v8, v18, v31
	v_lshlrev_b32_e32 v12, 2, v8
	v_mov_b32_e32 v13, v177
	v_lshl_add_u64 v[12:13], v[20:21], 0, v[12:13]
	s_and_saveexec_b64 s[2:3], s[4:5]
	s_cbranch_execz .LBB0_244
	v_lshlrev_b32_sdwa v8, v213, v22 dst_sel:DWORD dst_unused:UNUSED_PAD src0_sel:DWORD src1_sel:BYTE_0
	v_add_u32_e32 v9, v28, v8
	ds_read_b32 v9, v9 offset:16380
	v_readlane_b32 s4, v254, 21
	v_lshlrev_b64 v[10:11], 8, v[16:17]
	v_readlane_b32 s5, v254, 22
	s_waitcnt lgkmcnt(0)
	s_nop 0
	v_exp_f32_e32 v12, v9
	v_lshl_add_u64 v[10:11], s[4:5], 0, v[10:11]
	v_mov_b32_e32 v9, v177
	v_lshl_add_u64 v[8:9], v[10:11], 0, v[8:9]
	global_store_dword v[8:9], v12, off
.LBB0_244:
	s_or_b64 exec, exec, s[2:3]
	s_movk_i32 s2, 0x1040
	v_mad_u32_u24 v23, v27, s2, v28
	v_add_u32_e32 v8, 0xfffffefc, v23
	v_cmp_eq_u32_e64 s[36:37], 0, v27
	v_cmp_ne_u32_e32 vcc, 0, v27
	v_mov_b32_e32 v32, 0
	v_lshl_add_u32 v50, v29, 2, v8
	v_mov_b32_e32 v33, 0
	s_and_saveexec_b64 s[2:3], vcc
	ds_read_b32 v33, v50
	s_or_b64 exec, exec, s[2:3]
	v_lshlrev_b32_e32 v49, 2, v29
	s_and_saveexec_b64 s[2:3], vcc
	s_movk_i32 s4, 0xff00
	v_add3_u32 v8, v23, v49, s4
	ds_read_b32 v32, v8
	s_or_b64 exec, exec, s[2:3]
	v_mul_u32_u24_e32 v8, 0x104, v19
	v_add3_u32 v22, v28, v8, v49
	ds_read2_b32 v[8:9], v22 offset1:1
	v_mov_b32_e32 v36, 0
	v_mov_b32_e32 v38, 0
	s_and_saveexec_b64 s[2:3], vcc
	ds_read_b32 v38, v50 offset:8
	s_or_b64 exec, exec, s[2:3]
	s_and_saveexec_b64 s[2:3], vcc
	s_movk_i32 s4, 0xff08
	v_add3_u32 v10, v23, v49, s4
	ds_read_b32 v36, v10
	s_or_b64 exec, exec, s[2:3]
	ds_read2_b32 v[10:11], v22 offset0:2 offset1:3
	v_mov_b32_e32 v39, 0
	v_mov_b32_e32 v42, 0
	s_and_saveexec_b64 s[2:3], vcc
	ds_read_b32 v42, v50 offset:16
	s_or_b64 exec, exec, s[2:3]
	s_and_saveexec_b64 s[2:3], vcc
	s_movk_i32 s4, 0xff10
	v_add3_u32 v12, v23, v49, s4
	ds_read_b32 v39, v12
	s_or_b64 exec, exec, s[2:3]
	ds_read2_b32 v[12:13], v22 offset0:4 offset1:5
	v_mov_b32_e32 v44, 0
	v_mov_b32_e32 v46, 0
	s_and_saveexec_b64 s[2:3], vcc
	ds_read_b32 v46, v50 offset:24
	s_or_b64 exec, exec, s[2:3]
	s_and_saveexec_b64 s[2:3], vcc
	s_movk_i32 s4, 0xff18
	v_add3_u32 v14, v23, v49, s4
	ds_read_b32 v44, v14
	s_or_b64 exec, exec, s[2:3]
	ds_read2_b32 v[14:15], v22 offset0:6 offset1:7
	v_mov_b32_e32 v34, 0
	v_mov_b32_e32 v35, 0
	s_and_saveexec_b64 s[2:3], vcc
	ds_read_b32 v35, v50 offset:128
	s_or_b64 exec, exec, s[2:3]
	s_and_saveexec_b64 s[2:3], vcc
	s_movk_i32 s4, 0xff80
	v_add3_u32 v16, v23, v49, s4
	ds_read_b32 v34, v16
	s_or_b64 exec, exec, s[2:3]
	ds_read2_b32 v[16:17], v22 offset0:32 offset1:33
	v_mov_b32_e32 v37, 0
	v_mov_b32_e32 v40, 0
	s_and_saveexec_b64 s[2:3], vcc
	ds_read_b32 v40, v50 offset:136
	s_or_b64 exec, exec, s[2:3]
	s_and_saveexec_b64 s[2:3], vcc
	s_movk_i32 s4, 0xff88
	v_add3_u32 v18, v23, v49, s4
	ds_read_b32 v37, v18
	s_or_b64 exec, exec, s[2:3]
	ds_read2_b32 v[18:19], v22 offset0:34 offset1:35
	v_mov_b32_e32 v41, 0
	v_mov_b32_e32 v43, 0
	s_and_saveexec_b64 s[2:3], vcc
	ds_read_b32 v43, v50 offset:144
	s_or_b64 exec, exec, s[2:3]
	s_and_saveexec_b64 s[2:3], vcc
	s_movk_i32 s4, 0xff90
	v_add3_u32 v20, v23, v49, s4
	ds_read_b32 v41, v20
	s_or_b64 exec, exec, s[2:3]
	ds_read2_b32 v[20:21], v22 offset0:36 offset1:37
	v_mov_b32_e32 v45, 0
	v_mov_b32_e32 v47, 0
	s_and_saveexec_b64 s[2:3], vcc
	ds_read_b32 v47, v50 offset:152
	s_or_b64 exec, exec, s[2:3]
	s_and_saveexec_b64 s[2:3], vcc
	s_movk_i32 s4, 0xff98
	v_add3_u32 v23, v23, v49, s4
	ds_read_b32 v45, v23
	s_or_b64 exec, exec, s[2:3]
	s_waitcnt lgkmcnt(2)
	v_sub_f32_e32 v23, v16, v35
	s_nop 0
	v_exp_f32_e32 v52, v23
	v_sub_f32_e32 v23, v17, v34
	s_nop 0
	s_nop 0
	v_exp_f32_e32 v16, v16
	v_exp_f32_e32 v17, v17
	s_nop 0
	v_exp_f32_e32 v53, v23
	v_lshlrev_b32_e32 v54, 16, v0
	v_and_b32_e32 v55, 0xffff0000, v0
	v_pk_mul_f32 v[16:17], v[16:17], v[54:55]
	v_pk_mul_f32 v[52:53], v[52:53], v[54:55]
	v_cvt_pk_bf16_f32 v16, v16, v17
	s_waitcnt lgkmcnt(1)
	v_sub_f32_e32 v17, v18, v40
	s_nop 0
	v_cvt_pk_bf16_f32 v0, v52, v53
	v_exp_f32_e32 v52, v17
	v_sub_f32_e32 v17, v19, v37
	s_nop 0
	v_exp_f32_e32 v53, v17
	v_mov_b32_e32 v17, v18
	v_exp_f32_e32 v18, v17
	v_mov_b32_e32 v17, v19
	v_exp_f32_e32 v19, v17
	v_lshlrev_b32_e32 v54, 16, v1
	v_and_b32_e32 v55, 0xffff0000, v1
	v_pk_mul_f32 v[52:53], v[52:53], v[54:55]
	v_pk_mul_f32 v[18:19], v[18:19], v[54:55]
	v_cvt_pk_bf16_f32 v1, v52, v53
	v_cvt_pk_bf16_f32 v17, v18, v19
	s_waitcnt lgkmcnt(0)
	v_sub_f32_e32 v18, v20, v43
	v_sub_f32_e32 v19, v21, v41
	s_nop 0
	s_nop 0
	v_exp_f32_e32 v18, v18
	v_exp_f32_e32 v19, v19
	s_nop 0
	s_nop 0
	v_exp_f32_e32 v20, v20
	v_exp_f32_e32 v21, v21
	v_lshlrev_b32_e32 v52, 16, v2
	v_and_b32_e32 v53, 0xffff0000, v2
	v_pk_mul_f32 v[18:19], v[18:19], v[52:53]
	s_movk_i32 s4, 0x300
	v_cvt_pk_bf16_f32 v2, v18, v19
	v_pk_mul_f32 v[18:19], v[20:21], v[52:53]
	v_lshlrev_b32_e32 v52, 16, v4
	v_cvt_pk_bf16_f32 v18, v18, v19
	v_sub_f32_e32 v19, v8, v33
	s_nop 0
	v_exp_f32_e32 v20, v19
	v_sub_f32_e32 v19, v9, v32
	s_nop 0
	s_nop 0
	v_exp_f32_e32 v8, v8
	v_exp_f32_e32 v9, v9
	s_nop 0
	v_exp_f32_e32 v21, v19
	v_and_b32_e32 v53, 0xffff0000, v4
	v_pk_mul_f32 v[8:9], v[8:9], v[52:53]
	v_or_b32_e32 v50, 2, v30
	v_cvt_pk_bf16_f32 v8, v8, v9
	v_sub_f32_e32 v9, v10, v38
	v_pk_mul_f32 v[20:21], v[20:21], v[52:53]
	s_nop 0
	v_cvt_pk_bf16_f32 v4, v20, v21
	v_exp_f32_e32 v20, v9
	v_sub_f32_e32 v9, v11, v36
	s_nop 0
	v_exp_f32_e32 v21, v9
	v_mov_b32_e32 v9, v10
	v_exp_f32_e32 v10, v9
	v_mov_b32_e32 v9, v11
	v_exp_f32_e32 v11, v9
	v_lshlrev_b32_e32 v52, 16, v5
	v_and_b32_e32 v53, 0xffff0000, v5
	v_pk_mul_f32 v[20:21], v[20:21], v[52:53]
	v_pk_mul_f32 v[10:11], v[10:11], v[52:53]
	v_cvt_pk_bf16_f32 v5, v20, v21
	v_cvt_pk_bf16_f32 v9, v10, v11
	v_sub_f32_e32 v10, v12, v42
	v_sub_f32_e32 v11, v13, v39
	s_nop 0
	s_nop 0
	v_exp_f32_e32 v10, v10
	v_exp_f32_e32 v11, v11
	s_nop 0
	s_nop 0
	v_exp_f32_e32 v12, v12
	v_exp_f32_e32 v13, v13
	v_lshlrev_b32_e32 v20, 16, v6
	v_and_b32_e32 v21, 0xffff0000, v6
	v_pk_mul_f32 v[10:11], v[10:11], v[20:21]
	v_or_b32_e32 v49, 3, v30
	v_cvt_pk_bf16_f32 v6, v10, v11
	v_pk_mul_f32 v[10:11], v[12:13], v[20:21]
	v_lshlrev_b32_e32 v20, 16, v7
	v_cvt_pk_bf16_f32 v10, v10, v11
	v_sub_f32_e32 v11, v14, v46
	s_nop 0
	v_exp_f32_e32 v12, v11
	v_sub_f32_e32 v11, v15, v44
	s_nop 0
	v_exp_f32_e32 v13, v11
	v_mov_b32_e32 v11, v14
	v_exp_f32_e32 v14, v11
	v_mov_b32_e32 v11, v15
	v_exp_f32_e32 v15, v11
	v_and_b32_e32 v21, 0xffff0000, v7
	v_pk_mul_f32 v[12:13], v[12:13], v[20:21]
	s_nop 0
	v_cvt_pk_bf16_f32 v7, v12, v13
	v_pk_mul_f32 v[12:13], v[14:15], v[20:21]
	v_lshlrev_b32_e32 v20, 16, v3
	v_cvt_pk_bf16_f32 v11, v12, v13
	ds_read2_b32 v[12:13], v22 offset0:38 offset1:39
	v_and_b32_e32 v21, 0xffff0000, v3
	s_waitcnt lgkmcnt(0)
	v_sub_f32_e32 v14, v12, v47
	v_sub_f32_e32 v15, v13, v45
	s_nop 0
	s_nop 0
	v_exp_f32_e32 v12, v12
	v_exp_f32_e32 v13, v13
	s_nop 0
	s_nop 0
	v_exp_f32_e32 v14, v14
	v_exp_f32_e32 v15, v15
	v_pk_mul_f32 v[12:13], v[12:13], v[20:21]
	v_pk_mul_f32 v[14:15], v[14:15], v[20:21]
	v_cvt_pk_bf16_f32 v19, v12, v13
	v_mov_b64_e32 v[12:13], s[64:65]
	v_mad_u64_u32 v[12:13], s[2:3], v24, s4, v[12:13]
	v_cvt_pk_bf16_f32 v3, v14, v15
	v_mov_b32_e32 v14, v13
	v_mad_u64_u32 v[14:15], s[2:3], v25, s4, v[14:15]
	v_mov_b32_e32 v13, v14
	v_lshl_add_u64 v[12:13], v[12:13], 0, v[176:177]
	v_lshlrev_b32_e32 v14, 1, v29
	v_mov_b32_e32 v15, v177
	v_lshl_add_u64 v[12:13], v[12:13], 0, v[14:15]
	s_movk_i32 s2, 0x41
	global_store_dwordx4 v[12:13], v[8:11], off sc1
	global_store_dwordx4 v[12:13], v[16:19], off offset:64 sc1
	s_nop 0
	v_mad_u32_u24 v8, v26, s2, v29
	v_lshl_add_u32 v15, v8, 2, v28
	ds_read2_b32 v[8:9], v15 offset1:1
	v_add_u32_e32 v10, 0x4400, v15
	ds_read2_b32 v[10:11], v10 offset1:1
	v_add_u32_e32 v14, 0x4480, v15
	s_waitcnt lgkmcnt(1)
	v_sub_f32_e32 v8, v33, v8
	v_sub_f32_e32 v9, v32, v9
	v_min_f32_e32 v8, 0x42e6d4ca, v8
	v_min_f32_e32 v9, 0x42e6d4ca, v9
	s_nop 0
	s_nop 0
	v_exp_f32_e32 v8, v8
	v_exp_f32_e32 v9, v9
	s_waitcnt lgkmcnt(0)
	v_pk_mul_f32 v[8:9], v[10:11], v[8:9]
	ds_read2_b32 v[10:11], v15 offset0:2 offset1:3
	v_cvt_pk_bf16_f32 v8, v8, v9
	v_add_u32_e32 v9, 0x4408, v15
	ds_read2_b32 v[12:13], v9 offset1:1
	s_waitcnt lgkmcnt(1)
	v_sub_f32_e32 v10, v38, v10
	v_sub_f32_e32 v11, v36, v11
	v_min_f32_e32 v10, 0x42e6d4ca, v10
	v_min_f32_e32 v11, 0x42e6d4ca, v11
	s_nop 0
	s_nop 0
	v_exp_f32_e32 v10, v10
	v_exp_f32_e32 v11, v11
	s_waitcnt lgkmcnt(0)
	v_pk_mul_f32 v[10:11], v[12:13], v[10:11]
	s_nop 0
	v_cvt_pk_bf16_f32 v9, v10, v11
	ds_read2_b32 v[10:11], v15 offset0:4 offset1:5
	v_add_u32_e32 v12, 0x4410, v15
	ds_read2_b32 v[12:13], v12 offset1:1
	s_waitcnt lgkmcnt(1)
	v_sub_f32_e32 v10, v42, v10
	v_sub_f32_e32 v11, v39, v11
	v_min_f32_e32 v10, 0x42e6d4ca, v10
	v_min_f32_e32 v11, 0x42e6d4ca, v11
	s_nop 0
	s_nop 0
	v_exp_f32_e32 v10, v10
	v_exp_f32_e32 v11, v11
	s_waitcnt lgkmcnt(0)
	v_pk_mul_f32 v[10:11], v[12:13], v[10:11]
	ds_read2_b32 v[12:13], v15 offset0:6 offset1:7
	v_cvt_pk_bf16_f32 v10, v10, v11
	v_add_u32_e32 v11, 0x4418, v15
	ds_read2_b32 v[16:17], v11 offset1:1
	s_waitcnt lgkmcnt(1)
	v_sub_f32_e32 v12, v46, v12
	v_sub_f32_e32 v13, v44, v13
	v_min_f32_e32 v12, 0x42e6d4ca, v12
	v_min_f32_e32 v13, 0x42e6d4ca, v13
	s_nop 0
	s_nop 0
	v_exp_f32_e32 v12, v12
	v_exp_f32_e32 v13, v13
	s_waitcnt lgkmcnt(0)
	v_pk_mul_f32 v[12:13], v[16:17], v[12:13]
	s_nop 0
	v_cvt_pk_bf16_f32 v11, v12, v13
	ds_read2_b32 v[12:13], v15 offset0:32 offset1:33
	ds_read2_b32 v[16:17], v14 offset1:1
	v_mfma_f32_16x16x32_bf16 v[8:11], v[8:11], v[4:7], 0
	s_waitcnt lgkmcnt(1)
	v_sub_f32_e32 v12, v35, v12
	v_sub_f32_e32 v13, v34, v13
	v_min_f32_e32 v12, 0x42e6d4ca, v12
	v_min_f32_e32 v13, 0x42e6d4ca, v13
	s_nop 0
	s_nop 0
	v_exp_f32_e32 v12, v12
	v_exp_f32_e32 v13, v13
	s_waitcnt lgkmcnt(0)
	v_pk_mul_f32 v[12:13], v[16:17], v[12:13]
	ds_read2_b32 v[16:17], v15 offset0:34 offset1:35
	v_cvt_pk_bf16_f32 v12, v12, v13
	v_add_u32_e32 v13, 0x4488, v15
	ds_read2_b32 v[18:19], v13 offset1:1
	s_waitcnt lgkmcnt(1)
	v_sub_f32_e32 v14, v40, v16
	v_min_f32_e32 v14, 0x42e6d4ca, v14
	s_nop 0
	v_exp_f32_e32 v16, v14
	v_sub_f32_e32 v14, v37, v17
	v_min_f32_e32 v14, 0x42e6d4ca, v14
	s_nop 0
	v_exp_f32_e32 v17, v14
	v_add_u32_e32 v14, 0x4490, v15
	s_waitcnt lgkmcnt(0)
	v_pk_mul_f32 v[16:17], v[18:19], v[16:17]
	s_nop 0
	v_cvt_pk_bf16_f32 v13, v16, v17
	ds_read2_b32 v[16:17], v15 offset0:36 offset1:37
	ds_read2_b32 v[18:19], v14 offset1:1
	s_waitcnt lgkmcnt(1)
	v_sub_f32_e32 v16, v43, v16
	v_sub_f32_e32 v17, v41, v17
	v_min_f32_e32 v16, 0x42e6d4ca, v16
	v_min_f32_e32 v17, 0x42e6d4ca, v17
	s_nop 0
	s_nop 0
	v_exp_f32_e32 v16, v16
	v_exp_f32_e32 v17, v17
	s_waitcnt lgkmcnt(0)
	v_pk_mul_f32 v[16:17], v[18:19], v[16:17]
	s_nop 0
	v_cvt_pk_bf16_f32 v14, v16, v17
	ds_read2_b32 v[16:17], v15 offset0:38 offset1:39
	v_add_u32_e32 v18, 0x4498, v15
	ds_read2_b32 v[18:19], v18 offset1:1
	s_waitcnt lgkmcnt(1)
	v_sub_f32_e32 v15, v47, v16
	v_min_f32_e32 v15, 0x42e6d4ca, v15
	s_nop 0
	v_exp_f32_e32 v16, v15
	v_sub_f32_e32 v15, v45, v17
	v_min_f32_e32 v15, 0x42e6d4ca, v15
	s_nop 0
	v_exp_f32_e32 v17, v15
	s_waitcnt lgkmcnt(0)
	v_pk_mul_f32 v[16:17], v[18:19], v[16:17]
	s_nop 0
	v_cvt_pk_bf16_f32 v15, v16, v17
	v_mov_b32_e32 v16, 0
	s_nop 0
	v_mfma_f32_16x16x32_bf16 v[8:11], v[12:15], v[0:3], v[8:11]
	s_and_saveexec_b64 s[2:3], s[36:37]
	v_cmp_gt_u32_e64 s[36:37], v30, v26
	s_nop 5
	v_cndmask_b32_e64 v12, v8, 0, s[36:37]
	v_cmp_lt_u32_e64 s[36:37], v30, v26
	s_nop 1
	v_cndmask_b32_e64 v8, v12, v8, s[36:37]
	v_cndmask_b32_e64 v9, 0, v9, s[36:37]
	v_cmp_le_u32_e64 s[36:37], v50, v26
	s_nop 1
	v_cndmask_b32_e64 v10, 0, v10, s[36:37]
	v_cmp_le_u32_e64 s[36:37], v49, v26
	s_nop 1
	v_cndmask_b32_e64 v11, 0, v11, s[36:37]
	s_or_b64 exec, exec, s[2:3]
	v_mov_b32_e32 v20, 0
	v_mov_b32_e32 v21, 0
	v_mov_b32_e32 v22, 0
	v_mov_b32_e32 v23, 0
	s_and_saveexec_b64 s[4:5], vcc
	s_cbranch_execz .LBB0_282
	s_movk_i32 s2, 0x41
	v_mad_u32_u24 v12, v51, s2, v29
	v_lshl_add_u32 v17, v12, 2, v28
	ds_read2_b32 v[80:81], v17 offset1:1
	v_add_u32_e32 v175, 0x4400, v17
	ds_read2_b32 v[82:83], v175 offset1:1
	ds_read2_b32 v[84:85], v17 offset0:2 offset1:3
	v_add_u32_e32 v174, 0x4408, v17
	ds_read2_b32 v[86:87], v174 offset1:1
	ds_read2_b32 v[88:89], v17 offset0:4 offset1:5
	v_add_u32_e32 v173, 0x4410, v17
	ds_read2_b32 v[90:91], v173 offset1:1
	ds_read2_b32 v[92:93], v17 offset0:6 offset1:7
	v_add_u32_e32 v172, 0x4418, v17
	ds_read2_b32 v[94:95], v172 offset1:1
	ds_read2_b32 v[96:97], v17 offset0:32 offset1:33
	v_add_u32_e32 v171, 0x4480, v17
	ds_read2_b32 v[98:99], v171 offset1:1
	ds_read2_b32 v[100:101], v17 offset0:34 offset1:35
	v_add_u32_e32 v170, 0x4488, v17
	ds_read2_b32 v[102:103], v170 offset1:1
	ds_read2_b32 v[104:105], v17 offset0:36 offset1:37
	v_add_u32_e32 v169, 0x4490, v17
	ds_read2_b32 v[106:107], v169 offset1:1
	ds_read2_b32 v[108:109], v17 offset0:38 offset1:39
	v_add_u32_e32 v168, 0x4498, v17
	ds_read2_b32 v[110:111], v168 offset1:1
	v_cmp_eq_u32_e32 vcc, 1, v27
	s_waitcnt lgkmcnt(1)
	v_sub_f32_e32 v12, v33, v80
	v_sub_f32_e32 v13, v32, v81
	v_min_f32_e32 v12, 0x42e6d4ca, v12
	v_min_f32_e32 v13, 0x42e6d4ca, v13
	s_nop 0
	s_nop 0
	v_exp_f32_e32 v12, v12
	v_exp_f32_e32 v13, v13
	s_waitcnt lgkmcnt(0)
	v_pk_mul_f32 v[12:13], v[82:83], v[12:13]
	v_cvt_pk_bf16_f32 v12, v12, v13
	s_waitcnt lgkmcnt(1)
	v_sub_f32_e32 v14, v38, v84
	v_sub_f32_e32 v15, v36, v85
	v_min_f32_e32 v14, 0x42e6d4ca, v14
	v_min_f32_e32 v15, 0x42e6d4ca, v15
	s_nop 0
	s_nop 0
	v_exp_f32_e32 v14, v14
	v_exp_f32_e32 v15, v15
	s_waitcnt lgkmcnt(0)
	v_pk_mul_f32 v[14:15], v[86:87], v[14:15]
	s_nop 0
	v_cvt_pk_bf16_f32 v13, v14, v15
	s_waitcnt lgkmcnt(1)
	v_sub_f32_e32 v14, v42, v88
	v_sub_f32_e32 v15, v39, v89
	v_min_f32_e32 v14, 0x42e6d4ca, v14
	v_min_f32_e32 v15, 0x42e6d4ca, v15
	s_nop 0
	s_nop 0
	v_exp_f32_e32 v14, v14
	v_exp_f32_e32 v15, v15
	s_waitcnt lgkmcnt(0)
	v_pk_mul_f32 v[14:15], v[90:91], v[14:15]
	v_cvt_pk_bf16_f32 v14, v14, v15
	s_waitcnt lgkmcnt(1)
	v_sub_f32_e32 v18, v46, v92
	v_sub_f32_e32 v19, v44, v93
	v_min_f32_e32 v18, 0x42e6d4ca, v18
	v_min_f32_e32 v19, 0x42e6d4ca, v19
	s_nop 0
	s_nop 0
	v_exp_f32_e32 v18, v18
	v_exp_f32_e32 v19, v19
	s_waitcnt lgkmcnt(0)
	v_pk_mul_f32 v[18:19], v[94:95], v[18:19]
	s_nop 0
	v_cvt_pk_bf16_f32 v15, v18, v19
	s_nop 1
	v_mfma_f32_16x16x32_bf16 v[12:15], v[12:15], v[4:7], 0
	s_waitcnt lgkmcnt(1)
	v_sub_f32_e32 v18, v35, v96
	v_sub_f32_e32 v19, v34, v97
	v_min_f32_e32 v18, 0x42e6d4ca, v18
	v_min_f32_e32 v19, 0x42e6d4ca, v19
	s_nop 0
	s_nop 0
	v_exp_f32_e32 v18, v18
	v_exp_f32_e32 v19, v19
	s_waitcnt lgkmcnt(0)
	v_pk_mul_f32 v[18:19], v[98:99], v[18:19]
	v_cvt_pk_bf16_f32 v18, v18, v19
	s_waitcnt lgkmcnt(1)
	v_sub_f32_e32 v20, v40, v100
	v_sub_f32_e32 v21, v37, v101
	v_min_f32_e32 v20, 0x42e6d4ca, v20
	v_min_f32_e32 v21, 0x42e6d4ca, v21
	s_nop 0
	s_nop 0
	v_exp_f32_e32 v20, v20
	v_exp_f32_e32 v21, v21
	s_waitcnt lgkmcnt(0)
	v_pk_mul_f32 v[20:21], v[102:103], v[20:21]
	s_nop 0
	v_cvt_pk_bf16_f32 v19, v20, v21
	s_waitcnt lgkmcnt(1)
	v_sub_f32_e32 v20, v43, v104
	v_sub_f32_e32 v21, v41, v105
	v_min_f32_e32 v20, 0x42e6d4ca, v20
	v_min_f32_e32 v21, 0x42e6d4ca, v21
	s_nop 0
	s_nop 0
	v_exp_f32_e32 v20, v20
	v_exp_f32_e32 v21, v21
	s_waitcnt lgkmcnt(0)
	v_pk_mul_f32 v[20:21], v[106:107], v[20:21]
	v_cvt_pk_bf16_f32 v20, v20, v21
	s_waitcnt lgkmcnt(1)
	v_sub_f32_e32 v17, v47, v108
	v_min_f32_e32 v17, 0x42e6d4ca, v17
	s_nop 0
	v_exp_f32_e32 v22, v17
	v_sub_f32_e32 v17, v45, v109
	v_min_f32_e32 v17, 0x42e6d4ca, v17
	s_nop 0
	v_exp_f32_e32 v23, v17
	s_waitcnt lgkmcnt(0)
	v_pk_mul_f32 v[22:23], v[110:111], v[22:23]
	s_nop 0
	v_cvt_pk_bf16_f32 v21, v22, v23
	s_nop 1
	v_mfma_f32_16x16x32_bf16 v[20:23], v[18:21], v[0:3], v[12:15]
	s_waitcnt lgkmcnt(0)
	v_mov_b32_e32 v52, v110
	v_mov_b32_e32 v53, v111
	s_and_saveexec_b64 s[2:3], vcc
	v_cmp_gt_u32_e32 vcc, v30, v26
	s_nop 5
	v_cndmask_b32_e64 v12, v20, 0, vcc
	v_cmp_lt_u32_e32 vcc, v30, v26
	s_nop 1
	v_cndmask_b32_e32 v20, v12, v20, vcc
	v_cndmask_b32_e32 v21, 0, v21, vcc
	v_cmp_le_u32_e32 vcc, v50, v26
	s_nop 1
	v_cndmask_b32_e32 v22, 0, v22, vcc
	v_cmp_le_u32_e32 vcc, v49, v26
	s_nop 1
	v_cndmask_b32_e32 v23, 0, v23, vcc
	s_or_b64 exec, exec, s[2:3]
.LBB0_282:
	s_or_b64 exec, exec, s[4:5]
	v_cmp_lt_u32_e32 vcc, 1, v27
	v_mov_b32_e32 v17, 0
	v_mov_b32_e32 v18, 0
	v_mov_b32_e32 v19, 0
	s_and_saveexec_b64 s[4:5], vcc
	s_cbranch_execz .LBB0_286
	s_movk_i32 s2, 0x41
	v_mad_u32_u24 v12, v48, s2, v29
	v_lshl_add_u32 v19, v12, 2, v28
	ds_read2_b32 v[80:81], v19 offset1:1
	v_add_u32_e32 v175, 0x4400, v19
	ds_read2_b32 v[82:83], v175 offset1:1
	ds_read2_b32 v[84:85], v19 offset0:2 offset1:3
	v_add_u32_e32 v174, 0x4408, v19
	ds_read2_b32 v[86:87], v174 offset1:1
	ds_read2_b32 v[88:89], v19 offset0:4 offset1:5
	v_add_u32_e32 v173, 0x4410, v19
	ds_read2_b32 v[90:91], v173 offset1:1
	ds_read2_b32 v[92:93], v19 offset0:6 offset1:7
	v_add_u32_e32 v172, 0x4418, v19
	ds_read2_b32 v[94:95], v172 offset1:1
	ds_read2_b32 v[96:97], v19 offset0:32 offset1:33
	v_add_u32_e32 v171, 0x4480, v19
	ds_read2_b32 v[98:99], v171 offset1:1
	ds_read2_b32 v[100:101], v19 offset0:34 offset1:35
	v_add_u32_e32 v170, 0x4488, v19
	ds_read2_b32 v[102:103], v170 offset1:1
	ds_read2_b32 v[104:105], v19 offset0:36 offset1:37
	v_add_u32_e32 v169, 0x4490, v19
	ds_read2_b32 v[106:107], v169 offset1:1
	ds_read2_b32 v[108:109], v19 offset0:38 offset1:39
	v_add_u32_e32 v168, 0x4498, v19
	ds_read2_b32 v[110:111], v168 offset1:1
	v_cmp_eq_u32_e64 s[36:37], 2, v27
	s_waitcnt lgkmcnt(1)
	v_sub_f32_e32 v12, v33, v80
	v_sub_f32_e32 v13, v32, v81
	v_min_f32_e32 v12, 0x42e6d4ca, v12
	v_min_f32_e32 v13, 0x42e6d4ca, v13
	s_nop 0
	s_nop 0
	v_exp_f32_e32 v12, v12
	v_exp_f32_e32 v13, v13
	s_waitcnt lgkmcnt(0)
	v_pk_mul_f32 v[12:13], v[82:83], v[12:13]
	v_cvt_pk_bf16_f32 v12, v12, v13
	s_waitcnt lgkmcnt(1)
	v_sub_f32_e32 v14, v38, v84
	v_sub_f32_e32 v15, v36, v85
	v_min_f32_e32 v14, 0x42e6d4ca, v14
	v_min_f32_e32 v15, 0x42e6d4ca, v15
	s_nop 0
	s_nop 0
	v_exp_f32_e32 v14, v14
	v_exp_f32_e32 v15, v15
	s_waitcnt lgkmcnt(0)
	v_pk_mul_f32 v[14:15], v[86:87], v[14:15]
	s_nop 0
	v_cvt_pk_bf16_f32 v13, v14, v15
	s_waitcnt lgkmcnt(1)
	v_sub_f32_e32 v14, v42, v88
	v_sub_f32_e32 v15, v39, v89
	v_min_f32_e32 v14, 0x42e6d4ca, v14
	v_min_f32_e32 v15, 0x42e6d4ca, v15
	s_nop 0
	s_nop 0
	v_exp_f32_e32 v14, v14
	v_exp_f32_e32 v15, v15
	s_waitcnt lgkmcnt(0)
	v_pk_mul_f32 v[14:15], v[90:91], v[14:15]
	v_cvt_pk_bf16_f32 v14, v14, v15
	s_waitcnt lgkmcnt(1)
	v_sub_f32_e32 v16, v46, v92
	v_sub_f32_e32 v17, v44, v93
	v_min_f32_e32 v16, 0x42e6d4ca, v16
	v_min_f32_e32 v17, 0x42e6d4ca, v17
	s_nop 0
	s_nop 0
	v_exp_f32_e32 v16, v16
	v_exp_f32_e32 v17, v17
	s_waitcnt lgkmcnt(0)
	v_pk_mul_f32 v[16:17], v[94:95], v[16:17]
	s_nop 0
	v_cvt_pk_bf16_f32 v15, v16, v17
	s_nop 1
	v_mfma_f32_16x16x32_bf16 v[12:15], v[12:15], v[4:7], 0
	s_waitcnt lgkmcnt(1)
	v_sub_f32_e32 v16, v35, v96
	v_sub_f32_e32 v17, v34, v97
	v_min_f32_e32 v16, 0x42e6d4ca, v16
	v_min_f32_e32 v17, 0x42e6d4ca, v17
	s_nop 0
	s_nop 0
	v_exp_f32_e32 v16, v16
	v_exp_f32_e32 v17, v17
	s_waitcnt lgkmcnt(0)
	v_pk_mul_f32 v[16:17], v[98:99], v[16:17]
	v_cvt_pk_bf16_f32 v16, v16, v17
	s_waitcnt lgkmcnt(1)
	v_sub_f32_e32 v18, v40, v100
	v_min_f32_e32 v18, 0x42e6d4ca, v18
	s_nop 0
	v_exp_f32_e32 v52, v18
	v_sub_f32_e32 v18, v37, v101
	v_min_f32_e32 v18, 0x42e6d4ca, v18
	s_nop 0
	v_exp_f32_e32 v53, v18
	s_waitcnt lgkmcnt(0)
	v_pk_mul_f32 v[52:53], v[102:103], v[52:53]
	s_nop 0
	v_cvt_pk_bf16_f32 v17, v52, v53
	s_waitcnt lgkmcnt(1)
	v_sub_f32_e32 v48, v43, v104
	v_min_f32_e32 v48, 0x42e6d4ca, v48
	s_nop 0
	v_exp_f32_e32 v52, v48
	v_sub_f32_e32 v48, v41, v105
	v_min_f32_e32 v48, 0x42e6d4ca, v48
	s_nop 0
	v_exp_f32_e32 v53, v48
	s_waitcnt lgkmcnt(0)
	v_pk_mul_f32 v[52:53], v[106:107], v[52:53]
	s_nop 0
	v_cvt_pk_bf16_f32 v18, v52, v53
	s_waitcnt lgkmcnt(1)
	v_sub_f32_e32 v19, v47, v108
	v_min_f32_e32 v19, 0x42e6d4ca, v19
	s_nop 0
	v_exp_f32_e32 v52, v19
	v_sub_f32_e32 v19, v45, v109
	v_min_f32_e32 v19, 0x42e6d4ca, v19
	s_nop 0
	v_exp_f32_e32 v53, v19
	s_waitcnt lgkmcnt(0)
	v_pk_mul_f32 v[52:53], v[110:111], v[52:53]
	s_nop 0
	v_cvt_pk_bf16_f32 v19, v52, v53
	s_nop 1
	v_mfma_f32_16x16x32_bf16 v[16:19], v[16:19], v[0:3], v[12:15]
	s_waitcnt lgkmcnt(0)
	v_mov_b32_e32 v54, v110
	v_mov_b32_e32 v55, v111
	s_and_saveexec_b64 s[2:3], s[36:37]
	v_cmp_gt_u32_e64 s[36:37], v30, v26
	s_nop 5
	v_cndmask_b32_e64 v12, v16, 0, s[36:37]
	v_cmp_lt_u32_e64 s[36:37], v30, v26
	s_nop 1
	v_cndmask_b32_e64 v16, v12, v16, s[36:37]
	v_cndmask_b32_e64 v17, 0, v17, s[36:37]
	v_cmp_le_u32_e64 s[36:37], v50, v26
	s_nop 1
	v_cndmask_b32_e64 v18, 0, v18, s[36:37]
	v_cmp_le_u32_e64 s[36:37], v49, v26
	s_nop 1
	v_cndmask_b32_e64 v19, 0, v19, s[36:37]
	s_or_b64 exec, exec, s[2:3]
.LBB0_286:
	s_or_b64 exec, exec, s[4:5]
	v_cmp_eq_u32_e64 s[36:37], 3, v27
	v_mov_b32_e32 v12, 0
	v_mov_b32_e32 v13, 0
	v_mov_b32_e32 v14, 0
	v_mov_b32_e32 v15, 0
	s_and_saveexec_b64 s[2:3], s[36:37]
	s_cbranch_execz .LBB0_288
	s_movk_i32 s4, 0x41
	v_mad_u32_u24 v12, v31, s4, v29
	v_lshl_add_u32 v27, v12, 2, v28
	ds_read2_b32 v[80:81], v27 offset1:1
	ds_read2_b32 v[82:83], v27 offset0:2 offset1:3
	ds_read2_b32 v[84:85], v27 offset0:4 offset1:5
	ds_read2_b32 v[86:87], v27 offset0:6 offset1:7
	v_add_u32_e32 v175, 0x4400, v27
	ds_read2_b32 v[88:89], v175 offset1:1
	v_add_u32_e32 v174, 0x4408, v27
	ds_read2_b32 v[90:91], v174 offset1:1
	v_add_u32_e32 v173, 0x4410, v27
	ds_read2_b32 v[92:93], v173 offset1:1
	v_add_u32_e32 v172, 0x4418, v27
	ds_read2_b32 v[94:95], v172 offset1:1
	ds_read2_b32 v[96:97], v27 offset0:32 offset1:33
	ds_read2_b32 v[98:99], v27 offset0:34 offset1:35
	ds_read2_b32 v[100:101], v27 offset0:36 offset1:37
	ds_read2_b32 v[102:103], v27 offset0:38 offset1:39
	v_add_u32_e32 v171, 0x4480, v27
	ds_read2_b32 v[104:105], v171 offset1:1
	v_add_u32_e32 v170, 0x4488, v27
	ds_read2_b32 v[106:107], v170 offset1:1
	v_add_u32_e32 v169, 0x4490, v27
	ds_read2_b32 v[108:109], v169 offset1:1
	v_add_u32_e32 v168, 0x4498, v27
	ds_read2_b32 v[110:111], v168 offset1:1
	v_cmp_lt_u32_e64 s[36:37], v30, v26
	s_waitcnt lgkmcnt(2)
	v_sub_f32_e32 v14, v38, v82
	v_sub_f32_e32 v12, v33, v80
	v_sub_f32_e32 v13, v32, v81
	v_min_f32_e32 v12, 0x42e6d4ca, v12
	v_min_f32_e32 v13, 0x42e6d4ca, v13
	s_nop 0
	s_nop 0
	v_exp_f32_e32 v12, v12
	v_exp_f32_e32 v13, v13
	v_sub_f32_e32 v15, v36, v83
	s_waitcnt lgkmcnt(0)
	v_pk_mul_f32 v[12:13], v[88:89], v[12:13]
	v_min_f32_e32 v14, 0x42e6d4ca, v14
	v_cvt_pk_bf16_f32 v12, v12, v13
	v_sub_f32_e32 v13, v42, v84
	v_min_f32_e32 v13, 0x42e6d4ca, v13
	s_nop 0
	v_exp_f32_e32 v32, v13
	v_sub_f32_e32 v13, v39, v85
	v_min_f32_e32 v13, 0x42e6d4ca, v13
	s_nop 0
	v_exp_f32_e32 v33, v13
	v_sub_f32_e32 v13, v46, v86
	v_min_f32_e32 v13, 0x42e6d4ca, v13
	s_nop 0
	v_min_f32_e32 v15, 0x42e6d4ca, v15
	v_exp_f32_e32 v38, v13
	v_sub_f32_e32 v13, v44, v87
	s_nop 0
	s_nop 0
	v_min_f32_e32 v13, 0x42e6d4ca, v13
	v_exp_f32_e32 v14, v14
	v_exp_f32_e32 v15, v15
	s_nop 0
	v_exp_f32_e32 v39, v13
	s_waitcnt lgkmcnt(2)
	v_pk_mul_f32 v[14:15], v[90:91], v[14:15]
	s_nop 0
	v_cvt_pk_bf16_f32 v13, v14, v15
	s_waitcnt lgkmcnt(1)
	v_pk_mul_f32 v[14:15], v[92:93], v[32:33]
	s_waitcnt lgkmcnt(0)
	v_pk_mul_f32 v[32:33], v[94:95], v[38:39]
	v_cvt_pk_bf16_f32 v14, v14, v15
	v_cvt_pk_bf16_f32 v15, v32, v33
	s_nop 1
	v_mfma_f32_16x16x32_bf16 v[4:7], v[12:15], v[4:7], 0
	s_waitcnt lgkmcnt(2)
	v_sub_f32_e32 v14, v40, v98
	v_sub_f32_e32 v12, v35, v96
	v_sub_f32_e32 v13, v34, v97
	v_min_f32_e32 v12, 0x42e6d4ca, v12
	v_min_f32_e32 v13, 0x42e6d4ca, v13
	s_nop 0
	s_nop 0
	v_exp_f32_e32 v12, v12
	v_exp_f32_e32 v13, v13
	v_sub_f32_e32 v15, v37, v99
	v_min_f32_e32 v14, 0x42e6d4ca, v14
	v_min_f32_e32 v15, 0x42e6d4ca, v15
	s_waitcnt lgkmcnt(0)
	v_pk_mul_f32 v[12:13], v[104:105], v[12:13]
	v_cvt_pk_bf16_f32 v12, v12, v13
	v_sub_f32_e32 v13, v43, v100
	v_min_f32_e32 v13, 0x42e6d4ca, v13
	s_nop 0
	v_exp_f32_e32 v32, v13
	v_sub_f32_e32 v13, v41, v101
	v_min_f32_e32 v13, 0x42e6d4ca, v13
	s_nop 0
	v_exp_f32_e32 v33, v13
	v_sub_f32_e32 v13, v47, v102
	v_min_f32_e32 v13, 0x42e6d4ca, v13
	s_nop 0
	v_exp_f32_e32 v34, v13
	v_sub_f32_e32 v13, v45, v103
	s_nop 0
	s_nop 0
	v_min_f32_e32 v13, 0x42e6d4ca, v13
	v_exp_f32_e32 v14, v14
	v_exp_f32_e32 v15, v15
	s_nop 0
	v_exp_f32_e32 v35, v13
	s_waitcnt lgkmcnt(2)
	v_pk_mul_f32 v[14:15], v[106:107], v[14:15]
	s_nop 0
	v_cvt_pk_bf16_f32 v13, v14, v15
	s_waitcnt lgkmcnt(1)
	v_pk_mul_f32 v[14:15], v[108:109], v[32:33]
	s_waitcnt lgkmcnt(0)
	v_pk_mul_f32 v[32:33], v[110:111], v[34:35]
	v_cvt_pk_bf16_f32 v14, v14, v15
	v_cvt_pk_bf16_f32 v15, v32, v33
	s_nop 1
	v_mfma_f32_16x16x32_bf16 v[0:3], v[12:15], v[0:3], v[4:7]
	s_nop 7
	v_cndmask_b32_e64 v13, 0, v1, s[36:37]
	v_cmp_le_u32_e64 s[36:37], v30, v26
	s_nop 1
	v_cndmask_b32_e64 v12, 0, v0, s[36:37]
	v_cmp_le_u32_e64 s[36:37], v50, v26
	s_nop 1
	v_cndmask_b32_e64 v14, 0, v2, s[36:37]
	v_cmp_le_u32_e64 s[36:37], v49, v26
	s_nop 1
	v_cndmask_b32_e64 v15, 0, v3, s[36:37]
	s_waitcnt lgkmcnt(0)
	v_mov_b32_e32 v36, v106
	v_mov_b32_e32 v37, v107
	v_mov_b32_e32 v38, v102
	v_mov_b32_e32 v39, v103
	v_mov_b32_e32 v52, v108
	v_mov_b32_e32 v53, v109
	v_mov_b32_e32 v54, v110
	v_mov_b32_e32 v55, v111
	v_mov_b32_e32 v56, v90
	v_mov_b32_e32 v57, v91
	v_mov_b32_e32 v58, v92
	v_mov_b32_e32 v59, v93
	v_mov_b32_e32 v60, v94
	v_mov_b32_e32 v61, v95
